# v2 + RS_IN GEMM epilogues: 8 rs_in row loads preloaded at epilogue entry (one wait instead of 8 load+vmcnt(0) round trips)
# speedup vs baseline: 1.0074x; 1.0056x over previous
.LBB0_735:
	v_lshl_or_b32 v146, s0, 8, v149
	v_ashrrev_i32_e32 v147, 31, v146
	v_lshl_add_u64 v[144:145], v[146:147], 2, s[14:15]
	global_load_dword v159, v[144:145], off
	global_load_dword v181, v[144:145], off offset:64
	global_load_dword v182, v[144:145], off offset:128
	global_load_dword v183, v[144:145], off offset:192
	global_load_dword v184, v[144:145], off offset:512
	global_load_dword v185, v[144:145], off offset:576
	global_load_dword v186, v[144:145], off offset:640
	global_load_dword v187, v[144:145], off offset:704
	v_lshlrev_b64 v[162:163], 14, v[146:147]
	v_lshl_or_b32 v144, s1, 8, v150
	v_ashrrev_i32_e32 v145, 31, v144
	v_or_b32_e32 v160, 16, v146
	v_lshlrev_b64 v[144:145], 1, v[144:145]
	v_lshl_add_u64 v[162:163], s[12:13], 0, v[162:163]
	v_ashrrev_i32_e32 v161, 31, v160
	v_lshl_add_u64 v[162:163], v[162:163], 0, v[144:145]
	v_lshl_add_u64 v[164:165], v[160:161], 2, s[14:15]
	s_waitcnt vmcnt(0)
	v_fmamk_f32 v147, v159, 0x3a000000, v154
	v_mul_f32_e32 v159, 0x4f800000, v147
	v_cmp_gt_f32_e32 vcc, s70, v147
	s_nop 1
	v_cndmask_b32_e32 v147, v147, v159, vcc
	v_sqrt_f32_e32 v159, v147
	s_nop 0
	v_add_u32_e32 v166, -1, v159
	v_add_u32_e32 v167, 1, v159
	v_fma_f32 v168, -v166, v159, v147
	v_fma_f32 v169, -v167, v159, v147
	v_cmp_ge_f32_e64 s[0:1], 0, v168
	s_nop 1
	v_cndmask_b32_e64 v159, v159, v166, s[0:1]
	v_cmp_lt_f32_e64 s[0:1], 0, v169
	s_nop 1
	v_cndmask_b32_e64 v159, v159, v167, s[0:1]
	v_mul_f32_e32 v166, 0x37800000, v159
	v_cndmask_b32_e32 v159, v159, v166, vcc
	v_cmp_class_f32_e32 vcc, v147, v155
	s_nop 1
	v_cndmask_b32_e32 v147, v159, v147, vcc
	v_div_scale_f32 v159, s[0:1], v147, v147, 1.0
	v_rcp_f32_e32 v166, v159
	v_div_scale_f32 v167, vcc, 1.0, v147, 1.0
	v_fma_f32 v168, -v159, v166, 1.0
	v_fmac_f32_e32 v166, v168, v166
	v_mul_f32_e32 v168, v167, v166
	v_fma_f32 v169, -v159, v168, v167
	v_fmac_f32_e32 v168, v169, v166
	v_fma_f32 v159, -v159, v168, v167
	v_div_fmas_f32 v159, v159, v166, v168
	v_div_fixup_f32 v166, v159, v147, 1.0
	v_pk_mul_f32 v[126:127], v[126:127], v[166:167] op_sel_hi:[1,0]
	v_pk_mul_f32 v[124:125], v[124:125], v[166:167] op_sel_hi:[1,0]
	v_pk_mul_f32 v[122:123], v[122:123], v[166:167] op_sel_hi:[1,0]
	v_pk_mul_f32 v[120:121], v[120:121], v[166:167] op_sel_hi:[1,0]
	v_pk_mul_f32 v[114:115], v[114:115], v[166:167] op_sel_hi:[1,0]
	v_pk_mul_f32 v[112:113], v[112:113], v[166:167] op_sel_hi:[1,0]
	v_pk_mul_f32 v[118:119], v[118:119], v[166:167] op_sel_hi:[1,0]
	v_pk_mul_f32 v[116:117], v[116:117], v[166:167] op_sel_hi:[1,0]
	v_max_f32_e32 v124, 0, v124
	v_max_f32_e32 v120, 0, v120
	v_max_f32_e32 v125, 0, v125
	v_max_f32_e32 v121, 0, v121
	v_max_f32_e32 v126, 0, v126
	v_max_f32_e32 v122, 0, v122
	v_max_f32_e32 v127, 0, v127
	v_max_f32_e32 v123, 0, v123
	v_max_f32_e32 v112, 0, v112
	v_max_f32_e32 v113, 0, v113
	v_max_f32_e32 v114, 0, v114
	v_max_f32_e32 v115, 0, v115
	v_max_f32_e32 v116, 0, v116
	v_max_f32_e32 v117, 0, v117
	v_max_f32_e32 v118, 0, v118
	v_max_f32_e32 v119, 0, v119
	v_mul_f32_e32 v124, v124, v124
	v_mul_f32_e32 v120, v120, v120
	v_mul_f32_e32 v125, v125, v125
	v_mul_f32_e32 v121, v121, v121
	v_mul_f32_e32 v126, v126, v126
	v_mul_f32_e32 v122, v122, v122
	v_mul_f32_e32 v127, v127, v127
	v_mul_f32_e32 v123, v123, v123
	v_mul_f32_e32 v147, v112, v112
	v_mul_f32_e32 v159, v113, v113
	v_mul_f32_e32 v166, v114, v114
	v_mul_f32_e32 v167, v115, v115
	v_cvt_pk_bf16_f32 v112, v124, v125
	v_cvt_pk_bf16_f32 v113, v126, v127
	v_cvt_pk_bf16_f32 v114, v120, v121
	v_cvt_pk_bf16_f32 v115, v122, v123
	v_mul_f32_e32 v116, v116, v116
	v_mul_f32_e32 v117, v117, v117
	v_mul_f32_e32 v118, v118, v118
	v_mul_f32_e32 v119, v119, v119
	global_store_dwordx4 v[162:163], v[112:115], off nt
	s_nop 1
	v_cvt_pk_bf16_f32 v112, v116, v117
	v_cvt_pk_bf16_f32 v113, v118, v119
	v_cvt_pk_bf16_f32 v114, v147, v159
	v_cvt_pk_bf16_f32 v115, v166, v167
	global_store_dwordx4 v[162:163], v[112:115], off offset:256 nt
	s_nop 1
	v_mov_b32_e32 v114, v181
	s_nop 0
	v_or_b32_e32 v112, 32, v146
	v_ashrrev_i32_e32 v113, 31, v112
	v_lshl_add_u64 v[116:117], v[112:113], 2, s[14:15]
	v_fmamk_f32 v114, v114, 0x3a000000, v154
	v_mul_f32_e32 v115, 0x4f800000, v114
	v_cmp_gt_f32_e32 vcc, s70, v114
	s_nop 1
	v_cndmask_b32_e32 v118, v114, v115, vcc
	v_sqrt_f32_e32 v119, v118
	v_lshlrev_b64 v[114:115], 14, v[160:161]
	v_lshl_add_u64 v[114:115], s[12:13], 0, v[114:115]
	v_lshl_add_u64 v[114:115], v[114:115], 0, v[144:145]
	v_add_u32_e32 v120, -1, v119
	v_add_u32_e32 v121, 1, v119
	v_fma_f32 v122, -v120, v119, v118
	v_fma_f32 v123, -v121, v119, v118
	v_cmp_ge_f32_e64 s[0:1], 0, v122
	s_nop 1
	v_cndmask_b32_e64 v119, v119, v120, s[0:1]
	v_cmp_lt_f32_e64 s[0:1], 0, v123
	s_nop 1
	v_cndmask_b32_e64 v119, v119, v121, s[0:1]
	v_mul_f32_e32 v120, 0x37800000, v119
	v_cndmask_b32_e32 v119, v119, v120, vcc
	v_cmp_class_f32_e32 vcc, v118, v155
	s_nop 1
	v_cndmask_b32_e32 v118, v119, v118, vcc
	v_div_scale_f32 v119, s[0:1], v118, v118, 1.0
	v_rcp_f32_e32 v120, v119
	v_div_scale_f32 v121, vcc, 1.0, v118, 1.0
	v_fma_f32 v122, -v119, v120, 1.0
	v_fmac_f32_e32 v120, v122, v120
	v_mul_f32_e32 v122, v121, v120
	v_fma_f32 v123, -v119, v122, v121
	v_fmac_f32_e32 v122, v123, v120
	v_fma_f32 v119, -v119, v122, v121
	v_div_fmas_f32 v119, v119, v120, v122
	v_div_fixup_f32 v118, v119, v118, 1.0
	v_pk_mul_f32 v[110:111], v[110:111], v[118:119] op_sel_hi:[1,0]
	v_pk_mul_f32 v[108:109], v[108:109], v[118:119] op_sel_hi:[1,0]
	v_pk_mul_f32 v[106:107], v[106:107], v[118:119] op_sel_hi:[1,0]
	v_pk_mul_f32 v[104:105], v[104:105], v[118:119] op_sel_hi:[1,0]
	v_pk_mul_f32 v[98:99], v[98:99], v[118:119] op_sel_hi:[1,0]
	v_pk_mul_f32 v[96:97], v[96:97], v[118:119] op_sel_hi:[1,0]
	v_pk_mul_f32 v[102:103], v[102:103], v[118:119] op_sel_hi:[1,0]
	v_pk_mul_f32 v[100:101], v[100:101], v[118:119] op_sel_hi:[1,0]
	v_max_f32_e32 v108, 0, v108
	v_max_f32_e32 v104, 0, v104
	v_max_f32_e32 v109, 0, v109
	v_max_f32_e32 v105, 0, v105
	v_max_f32_e32 v110, 0, v110
	v_max_f32_e32 v106, 0, v106
	v_max_f32_e32 v111, 0, v111
	v_max_f32_e32 v107, 0, v107
	v_max_f32_e32 v96, 0, v96
	v_max_f32_e32 v97, 0, v97
	v_max_f32_e32 v98, 0, v98
	v_max_f32_e32 v99, 0, v99
	v_max_f32_e32 v100, 0, v100
	v_max_f32_e32 v101, 0, v101
	v_max_f32_e32 v102, 0, v102
	v_max_f32_e32 v103, 0, v103
	v_mul_f32_e32 v108, v108, v108
	v_mul_f32_e32 v104, v104, v104
	v_mul_f32_e32 v109, v109, v109
	v_mul_f32_e32 v105, v105, v105
	v_mul_f32_e32 v110, v110, v110
	v_mul_f32_e32 v106, v106, v106
	v_mul_f32_e32 v111, v111, v111
	v_mul_f32_e32 v107, v107, v107
	v_mul_f32_e32 v118, v96, v96
	v_mul_f32_e32 v119, v97, v97
	v_mul_f32_e32 v120, v98, v98
	v_mul_f32_e32 v121, v99, v99
	v_cvt_pk_bf16_f32 v96, v108, v109
	v_cvt_pk_bf16_f32 v97, v110, v111
	v_cvt_pk_bf16_f32 v98, v104, v105
	v_cvt_pk_bf16_f32 v99, v106, v107
	v_mul_f32_e32 v100, v100, v100
	v_mul_f32_e32 v101, v101, v101
	v_mul_f32_e32 v102, v102, v102
	v_mul_f32_e32 v103, v103, v103
	global_store_dwordx4 v[114:115], v[96:99], off nt
	s_nop 1
	v_cvt_pk_bf16_f32 v96, v100, v101
	v_cvt_pk_bf16_f32 v97, v102, v103
	v_cvt_pk_bf16_f32 v98, v118, v119
	v_cvt_pk_bf16_f32 v99, v120, v121
	global_store_dwordx4 v[114:115], v[96:99], off offset:256 nt
	s_nop 1
	v_mov_b32_e32 v98, v182
	s_nop 0
	v_or_b32_e32 v96, 48, v146
	v_ashrrev_i32_e32 v97, 31, v96
	v_lshl_add_u64 v[100:101], v[96:97], 2, s[14:15]
	v_fmamk_f32 v98, v98, 0x3a000000, v154
	v_mul_f32_e32 v99, 0x4f800000, v98
	v_cmp_gt_f32_e32 vcc, s70, v98
	s_nop 1
	v_cndmask_b32_e32 v102, v98, v99, vcc
	v_sqrt_f32_e32 v103, v102
	v_lshlrev_b64 v[98:99], 14, v[112:113]
	v_lshl_add_u64 v[98:99], s[12:13], 0, v[98:99]
	v_lshl_add_u64 v[98:99], v[98:99], 0, v[144:145]
	v_add_u32_e32 v104, -1, v103
	v_add_u32_e32 v105, 1, v103
	v_fma_f32 v106, -v104, v103, v102
	v_fma_f32 v107, -v105, v103, v102
	v_cmp_ge_f32_e64 s[0:1], 0, v106
	s_nop 1
	v_cndmask_b32_e64 v103, v103, v104, s[0:1]
	v_cmp_lt_f32_e64 s[0:1], 0, v107
	s_nop 1
	v_cndmask_b32_e64 v103, v103, v105, s[0:1]
	v_mul_f32_e32 v104, 0x37800000, v103
	v_cndmask_b32_e32 v103, v103, v104, vcc
	v_cmp_class_f32_e32 vcc, v102, v155
	s_nop 1
	v_cndmask_b32_e32 v102, v103, v102, vcc
	v_div_scale_f32 v103, s[0:1], v102, v102, 1.0
	v_rcp_f32_e32 v104, v103
	v_div_scale_f32 v105, vcc, 1.0, v102, 1.0
	v_fma_f32 v106, -v103, v104, 1.0
	v_fmac_f32_e32 v104, v106, v104
	v_mul_f32_e32 v106, v105, v104
	v_fma_f32 v107, -v103, v106, v105
	v_fmac_f32_e32 v106, v107, v104
	v_fma_f32 v103, -v103, v106, v105
	v_div_fmas_f32 v103, v103, v104, v106
	v_div_fixup_f32 v102, v103, v102, 1.0
	v_pk_mul_f32 v[94:95], v[94:95], v[102:103] op_sel_hi:[1,0]
	v_pk_mul_f32 v[92:93], v[92:93], v[102:103] op_sel_hi:[1,0]
	v_pk_mul_f32 v[90:91], v[90:91], v[102:103] op_sel_hi:[1,0]
	v_pk_mul_f32 v[88:89], v[88:89], v[102:103] op_sel_hi:[1,0]
	v_pk_mul_f32 v[82:83], v[82:83], v[102:103] op_sel_hi:[1,0]
	v_pk_mul_f32 v[80:81], v[80:81], v[102:103] op_sel_hi:[1,0]
	v_pk_mul_f32 v[86:87], v[86:87], v[102:103] op_sel_hi:[1,0]
	v_pk_mul_f32 v[84:85], v[84:85], v[102:103] op_sel_hi:[1,0]
	v_max_f32_e32 v92, 0, v92
	v_max_f32_e32 v88, 0, v88
	v_max_f32_e32 v93, 0, v93
	v_max_f32_e32 v89, 0, v89
	v_max_f32_e32 v94, 0, v94
	v_max_f32_e32 v90, 0, v90
	v_max_f32_e32 v95, 0, v95
	v_max_f32_e32 v91, 0, v91
	v_max_f32_e32 v80, 0, v80
	v_max_f32_e32 v81, 0, v81
	v_max_f32_e32 v82, 0, v82
	v_max_f32_e32 v83, 0, v83
	v_max_f32_e32 v84, 0, v84
	v_max_f32_e32 v85, 0, v85
	v_max_f32_e32 v86, 0, v86
	v_max_f32_e32 v87, 0, v87
	v_mul_f32_e32 v92, v92, v92
	v_mul_f32_e32 v88, v88, v88
	v_mul_f32_e32 v93, v93, v93
	v_mul_f32_e32 v89, v89, v89
	v_mul_f32_e32 v94, v94, v94
	v_mul_f32_e32 v90, v90, v90
	v_mul_f32_e32 v95, v95, v95
	v_mul_f32_e32 v91, v91, v91
	v_mul_f32_e32 v102, v80, v80
	v_mul_f32_e32 v103, v81, v81
	v_mul_f32_e32 v104, v82, v82
	v_mul_f32_e32 v105, v83, v83
	v_cvt_pk_bf16_f32 v80, v92, v93
	v_cvt_pk_bf16_f32 v81, v94, v95
	v_cvt_pk_bf16_f32 v82, v88, v89
	v_cvt_pk_bf16_f32 v83, v90, v91
	v_mul_f32_e32 v84, v84, v84
	v_mul_f32_e32 v85, v85, v85
	v_mul_f32_e32 v86, v86, v86
	v_mul_f32_e32 v87, v87, v87
	global_store_dwordx4 v[98:99], v[80:83], off nt
	s_nop 1
	v_cvt_pk_bf16_f32 v80, v84, v85
	v_cvt_pk_bf16_f32 v81, v86, v87
	v_cvt_pk_bf16_f32 v82, v102, v103
	v_cvt_pk_bf16_f32 v83, v104, v105
	global_store_dwordx4 v[98:99], v[80:83], off offset:256 nt
	s_nop 1
	v_mov_b32_e32 v82, v183
	s_nop 0
	v_or_b32_e32 v80, 0x80, v146
	v_ashrrev_i32_e32 v81, 31, v80
	v_lshl_add_u64 v[84:85], v[80:81], 2, s[14:15]
	v_fmamk_f32 v82, v82, 0x3a000000, v154
	v_mul_f32_e32 v83, 0x4f800000, v82
	v_cmp_gt_f32_e32 vcc, s70, v82
	s_nop 1
	v_cndmask_b32_e32 v86, v82, v83, vcc
	v_sqrt_f32_e32 v87, v86
	v_lshlrev_b64 v[82:83], 14, v[96:97]
	v_lshl_add_u64 v[82:83], s[12:13], 0, v[82:83]
	v_lshl_add_u64 v[82:83], v[82:83], 0, v[144:145]
	v_add_u32_e32 v88, -1, v87
	v_add_u32_e32 v89, 1, v87
	v_fma_f32 v90, -v88, v87, v86
	v_fma_f32 v91, -v89, v87, v86
	v_cmp_ge_f32_e64 s[0:1], 0, v90
	s_nop 1
	v_cndmask_b32_e64 v87, v87, v88, s[0:1]
	v_cmp_lt_f32_e64 s[0:1], 0, v91
	s_nop 1
	v_cndmask_b32_e64 v87, v87, v89, s[0:1]
	v_mul_f32_e32 v88, 0x37800000, v87
	v_cndmask_b32_e32 v87, v87, v88, vcc
	v_cmp_class_f32_e32 vcc, v86, v155
	s_nop 1
	v_cndmask_b32_e32 v86, v87, v86, vcc
	v_div_scale_f32 v87, s[0:1], v86, v86, 1.0
	v_rcp_f32_e32 v88, v87
	v_div_scale_f32 v89, vcc, 1.0, v86, 1.0
	v_fma_f32 v90, -v87, v88, 1.0
	v_fmac_f32_e32 v88, v90, v88
	v_mul_f32_e32 v90, v89, v88
	v_fma_f32 v91, -v87, v90, v89
	v_fmac_f32_e32 v90, v91, v88
	v_fma_f32 v87, -v87, v90, v89
	v_div_fmas_f32 v87, v87, v88, v90
	v_div_fixup_f32 v86, v87, v86, 1.0
	v_pk_mul_f32 v[78:79], v[78:79], v[86:87] op_sel_hi:[1,0]
	v_pk_mul_f32 v[76:77], v[76:77], v[86:87] op_sel_hi:[1,0]
	v_pk_mul_f32 v[74:75], v[74:75], v[86:87] op_sel_hi:[1,0]
	v_pk_mul_f32 v[72:73], v[72:73], v[86:87] op_sel_hi:[1,0]
	v_pk_mul_f32 v[66:67], v[66:67], v[86:87] op_sel_hi:[1,0]
	v_pk_mul_f32 v[64:65], v[64:65], v[86:87] op_sel_hi:[1,0]
	v_pk_mul_f32 v[70:71], v[70:71], v[86:87] op_sel_hi:[1,0]
	v_pk_mul_f32 v[68:69], v[68:69], v[86:87] op_sel_hi:[1,0]
	v_max_f32_e32 v76, 0, v76
	v_max_f32_e32 v72, 0, v72
	v_max_f32_e32 v77, 0, v77
	v_max_f32_e32 v73, 0, v73
	v_max_f32_e32 v78, 0, v78
	v_max_f32_e32 v74, 0, v74
	v_max_f32_e32 v79, 0, v79
	v_max_f32_e32 v75, 0, v75
	v_max_f32_e32 v64, 0, v64
	v_max_f32_e32 v65, 0, v65
	v_max_f32_e32 v66, 0, v66
	v_max_f32_e32 v67, 0, v67
	v_max_f32_e32 v68, 0, v68
	v_max_f32_e32 v69, 0, v69
	v_max_f32_e32 v70, 0, v70
	v_max_f32_e32 v71, 0, v71
	v_mul_f32_e32 v76, v76, v76
	v_mul_f32_e32 v72, v72, v72
	v_mul_f32_e32 v77, v77, v77
	v_mul_f32_e32 v73, v73, v73
	v_mul_f32_e32 v78, v78, v78
	v_mul_f32_e32 v74, v74, v74
	v_mul_f32_e32 v79, v79, v79
	v_mul_f32_e32 v75, v75, v75
	v_mul_f32_e32 v86, v64, v64
	v_mul_f32_e32 v87, v65, v65
	v_mul_f32_e32 v88, v66, v66
	v_mul_f32_e32 v89, v67, v67
	v_cvt_pk_bf16_f32 v64, v76, v77
	v_cvt_pk_bf16_f32 v65, v78, v79
	v_cvt_pk_bf16_f32 v66, v72, v73
	v_cvt_pk_bf16_f32 v67, v74, v75
	v_mul_f32_e32 v68, v68, v68
	v_mul_f32_e32 v69, v69, v69
	v_mul_f32_e32 v70, v70, v70
	v_mul_f32_e32 v71, v71, v71
	global_store_dwordx4 v[82:83], v[64:67], off nt
	s_nop 1
	v_cvt_pk_bf16_f32 v64, v68, v69
	v_cvt_pk_bf16_f32 v65, v70, v71
	v_cvt_pk_bf16_f32 v66, v86, v87
	v_cvt_pk_bf16_f32 v67, v88, v89
	global_store_dwordx4 v[82:83], v[64:67], off offset:256 nt
	s_nop 1
	v_mov_b32_e32 v66, v184
	s_nop 0
	v_or_b32_e32 v64, 0x90, v146
	v_ashrrev_i32_e32 v65, 31, v64
	v_lshl_add_u64 v[68:69], v[64:65], 2, s[14:15]
	v_fmamk_f32 v66, v66, 0x3a000000, v154
	v_mul_f32_e32 v67, 0x4f800000, v66
	v_cmp_gt_f32_e32 vcc, s70, v66
	s_nop 1
	v_cndmask_b32_e32 v70, v66, v67, vcc
	v_sqrt_f32_e32 v71, v70
	v_lshlrev_b64 v[66:67], 14, v[80:81]
	v_lshl_add_u64 v[66:67], s[12:13], 0, v[66:67]
	v_lshl_add_u64 v[66:67], v[66:67], 0, v[144:145]
	v_add_u32_e32 v72, -1, v71
	v_add_u32_e32 v73, 1, v71
	v_fma_f32 v74, -v72, v71, v70
	v_fma_f32 v75, -v73, v71, v70
	v_cmp_ge_f32_e64 s[0:1], 0, v74
	s_nop 1
	v_cndmask_b32_e64 v71, v71, v72, s[0:1]
	v_cmp_lt_f32_e64 s[0:1], 0, v75
	s_nop 1
	v_cndmask_b32_e64 v71, v71, v73, s[0:1]
	v_mul_f32_e32 v72, 0x37800000, v71
	v_cndmask_b32_e32 v71, v71, v72, vcc
	v_cmp_class_f32_e32 vcc, v70, v155
	s_nop 1
	v_cndmask_b32_e32 v70, v71, v70, vcc
	v_div_scale_f32 v71, s[0:1], v70, v70, 1.0
	v_rcp_f32_e32 v72, v71
	v_div_scale_f32 v73, vcc, 1.0, v70, 1.0
	v_fma_f32 v74, -v71, v72, 1.0
	v_fmac_f32_e32 v72, v74, v72
	v_mul_f32_e32 v74, v73, v72
	v_fma_f32 v75, -v71, v74, v73
	v_fmac_f32_e32 v74, v75, v72
	v_fma_f32 v71, -v71, v74, v73
	v_div_fmas_f32 v71, v71, v72, v74
	v_div_fixup_f32 v70, v71, v70, 1.0
	v_pk_mul_f32 v[62:63], v[62:63], v[70:71] op_sel_hi:[1,0]
	v_pk_mul_f32 v[60:61], v[60:61], v[70:71] op_sel_hi:[1,0]
	v_pk_mul_f32 v[58:59], v[58:59], v[70:71] op_sel_hi:[1,0]
	v_pk_mul_f32 v[56:57], v[56:57], v[70:71] op_sel_hi:[1,0]
	v_pk_mul_f32 v[50:51], v[50:51], v[70:71] op_sel_hi:[1,0]
	v_pk_mul_f32 v[48:49], v[48:49], v[70:71] op_sel_hi:[1,0]
	v_pk_mul_f32 v[54:55], v[54:55], v[70:71] op_sel_hi:[1,0]
	v_pk_mul_f32 v[52:53], v[52:53], v[70:71] op_sel_hi:[1,0]
	v_max_f32_e32 v60, 0, v60
	v_max_f32_e32 v56, 0, v56
	v_max_f32_e32 v61, 0, v61
	v_max_f32_e32 v57, 0, v57
	v_max_f32_e32 v62, 0, v62
	v_max_f32_e32 v58, 0, v58
	v_max_f32_e32 v63, 0, v63
	v_max_f32_e32 v59, 0, v59
	v_max_f32_e32 v48, 0, v48
	v_max_f32_e32 v49, 0, v49
	v_max_f32_e32 v50, 0, v50
	v_max_f32_e32 v51, 0, v51
	v_max_f32_e32 v52, 0, v52
	v_max_f32_e32 v53, 0, v53
	v_max_f32_e32 v54, 0, v54
	v_max_f32_e32 v55, 0, v55
	v_mul_f32_e32 v60, v60, v60
	v_mul_f32_e32 v56, v56, v56
	v_mul_f32_e32 v61, v61, v61
	v_mul_f32_e32 v57, v57, v57
	v_mul_f32_e32 v62, v62, v62
	v_mul_f32_e32 v58, v58, v58
	v_mul_f32_e32 v63, v63, v63
	v_mul_f32_e32 v59, v59, v59
	v_mul_f32_e32 v70, v48, v48
	v_mul_f32_e32 v71, v49, v49
	v_mul_f32_e32 v72, v50, v50
	v_mul_f32_e32 v73, v51, v51
	v_cvt_pk_bf16_f32 v48, v60, v61
	v_cvt_pk_bf16_f32 v49, v62, v63
	v_cvt_pk_bf16_f32 v50, v56, v57
	v_cvt_pk_bf16_f32 v51, v58, v59
	v_mul_f32_e32 v52, v52, v52
	v_mul_f32_e32 v53, v53, v53
	v_mul_f32_e32 v54, v54, v54
	v_mul_f32_e32 v55, v55, v55
	global_store_dwordx4 v[66:67], v[48:51], off nt
	s_nop 1
	v_cvt_pk_bf16_f32 v48, v52, v53
	v_cvt_pk_bf16_f32 v49, v54, v55
	v_cvt_pk_bf16_f32 v50, v70, v71
	v_cvt_pk_bf16_f32 v51, v72, v73
	global_store_dwordx4 v[66:67], v[48:51], off offset:256 nt
	s_nop 1
	v_mov_b32_e32 v50, v185
	s_nop 0
	v_or_b32_e32 v48, 0xa0, v146
	v_ashrrev_i32_e32 v49, 31, v48
	v_lshl_add_u64 v[52:53], v[48:49], 2, s[14:15]
	v_fmamk_f32 v50, v50, 0x3a000000, v154
	v_mul_f32_e32 v51, 0x4f800000, v50
	v_cmp_gt_f32_e32 vcc, s70, v50
	s_nop 1
	v_cndmask_b32_e32 v54, v50, v51, vcc
	v_sqrt_f32_e32 v55, v54
	v_lshlrev_b64 v[50:51], 14, v[64:65]
	v_lshl_add_u64 v[50:51], s[12:13], 0, v[50:51]
	v_lshl_add_u64 v[50:51], v[50:51], 0, v[144:145]
	v_add_u32_e32 v56, -1, v55
	v_add_u32_e32 v57, 1, v55
	v_fma_f32 v58, -v56, v55, v54
	v_fma_f32 v59, -v57, v55, v54
	v_cmp_ge_f32_e64 s[0:1], 0, v58
	s_nop 1
	v_cndmask_b32_e64 v55, v55, v56, s[0:1]
	v_cmp_lt_f32_e64 s[0:1], 0, v59
	s_nop 1
	v_cndmask_b32_e64 v55, v55, v57, s[0:1]
	v_mul_f32_e32 v56, 0x37800000, v55
	v_cndmask_b32_e32 v55, v55, v56, vcc
	v_cmp_class_f32_e32 vcc, v54, v155
	s_nop 1
	v_cndmask_b32_e32 v54, v55, v54, vcc
	v_div_scale_f32 v55, s[0:1], v54, v54, 1.0
	v_rcp_f32_e32 v56, v55
	v_div_scale_f32 v57, vcc, 1.0, v54, 1.0
	v_fma_f32 v58, -v55, v56, 1.0
	v_fmac_f32_e32 v56, v58, v56
	v_mul_f32_e32 v58, v57, v56
	v_fma_f32 v59, -v55, v58, v57
	v_fmac_f32_e32 v58, v59, v56
	v_fma_f32 v55, -v55, v58, v57
	v_div_fmas_f32 v55, v55, v56, v58
	v_div_fixup_f32 v54, v55, v54, 1.0
	v_pk_mul_f32 v[46:47], v[46:47], v[54:55] op_sel_hi:[1,0]
	v_pk_mul_f32 v[44:45], v[44:45], v[54:55] op_sel_hi:[1,0]
	v_pk_mul_f32 v[42:43], v[42:43], v[54:55] op_sel_hi:[1,0]
	v_pk_mul_f32 v[40:41], v[40:41], v[54:55] op_sel_hi:[1,0]
	v_pk_mul_f32 v[34:35], v[34:35], v[54:55] op_sel_hi:[1,0]
	v_pk_mul_f32 v[32:33], v[32:33], v[54:55] op_sel_hi:[1,0]
	v_pk_mul_f32 v[38:39], v[38:39], v[54:55] op_sel_hi:[1,0]
	v_pk_mul_f32 v[36:37], v[36:37], v[54:55] op_sel_hi:[1,0]
	v_max_f32_e32 v44, 0, v44
	v_max_f32_e32 v40, 0, v40
	v_max_f32_e32 v45, 0, v45
	v_max_f32_e32 v41, 0, v41
	v_max_f32_e32 v46, 0, v46
	v_max_f32_e32 v42, 0, v42
	v_max_f32_e32 v47, 0, v47
	v_max_f32_e32 v43, 0, v43
	v_max_f32_e32 v32, 0, v32
	v_max_f32_e32 v33, 0, v33
	v_max_f32_e32 v34, 0, v34
	v_max_f32_e32 v35, 0, v35
	v_max_f32_e32 v36, 0, v36
	v_max_f32_e32 v37, 0, v37
	v_max_f32_e32 v38, 0, v38
	v_max_f32_e32 v39, 0, v39
	v_mul_f32_e32 v44, v44, v44
	v_mul_f32_e32 v40, v40, v40
	v_mul_f32_e32 v45, v45, v45
	v_mul_f32_e32 v41, v41, v41
	v_mul_f32_e32 v46, v46, v46
	v_mul_f32_e32 v42, v42, v42
	v_mul_f32_e32 v47, v47, v47
	v_mul_f32_e32 v43, v43, v43
	v_mul_f32_e32 v54, v32, v32
	v_mul_f32_e32 v55, v33, v33
	v_mul_f32_e32 v56, v34, v34
	v_mul_f32_e32 v57, v35, v35
	v_cvt_pk_bf16_f32 v32, v44, v45
	v_cvt_pk_bf16_f32 v33, v46, v47
	v_cvt_pk_bf16_f32 v34, v40, v41
	v_cvt_pk_bf16_f32 v35, v42, v43
	v_mul_f32_e32 v36, v36, v36
	v_mul_f32_e32 v37, v37, v37
	v_mul_f32_e32 v38, v38, v38
	v_mul_f32_e32 v39, v39, v39
	global_store_dwordx4 v[50:51], v[32:35], off nt
	s_nop 1
	v_cvt_pk_bf16_f32 v32, v36, v37
	v_cvt_pk_bf16_f32 v33, v38, v39
	v_cvt_pk_bf16_f32 v34, v54, v55
	v_cvt_pk_bf16_f32 v35, v56, v57
	global_store_dwordx4 v[50:51], v[32:35], off offset:256 nt
	s_nop 1
	v_mov_b32_e32 v34, v186
	s_nop 0
	v_or_b32_e32 v32, 0xb0, v146
	v_ashrrev_i32_e32 v33, 31, v32
	v_lshl_add_u64 v[36:37], v[32:33], 2, s[14:15]
	v_fmamk_f32 v34, v34, 0x3a000000, v154
	v_mul_f32_e32 v35, 0x4f800000, v34
	v_cmp_gt_f32_e32 vcc, s70, v34
	s_nop 1
	v_cndmask_b32_e32 v38, v34, v35, vcc
	v_sqrt_f32_e32 v39, v38
	v_lshlrev_b64 v[34:35], 14, v[48:49]
	v_lshl_add_u64 v[34:35], s[12:13], 0, v[34:35]
	v_lshl_add_u64 v[34:35], v[34:35], 0, v[144:145]
	v_add_u32_e32 v40, -1, v39
	v_add_u32_e32 v41, 1, v39
	v_fma_f32 v42, -v40, v39, v38
	v_fma_f32 v43, -v41, v39, v38
	v_cmp_ge_f32_e64 s[0:1], 0, v42
	s_nop 1
	v_cndmask_b32_e64 v39, v39, v40, s[0:1]
	v_cmp_lt_f32_e64 s[0:1], 0, v43
	s_nop 1
	v_cndmask_b32_e64 v39, v39, v41, s[0:1]
	v_mul_f32_e32 v40, 0x37800000, v39
	v_cndmask_b32_e32 v39, v39, v40, vcc
	v_cmp_class_f32_e32 vcc, v38, v155
	s_nop 1
	v_cndmask_b32_e32 v38, v39, v38, vcc
	v_div_scale_f32 v39, s[0:1], v38, v38, 1.0
	v_rcp_f32_e32 v40, v39
	v_div_scale_f32 v41, vcc, 1.0, v38, 1.0
	v_fma_f32 v42, -v39, v40, 1.0
	v_fmac_f32_e32 v40, v42, v40
	v_mul_f32_e32 v42, v41, v40
	v_fma_f32 v43, -v39, v42, v41
	v_fmac_f32_e32 v42, v43, v40
	v_fma_f32 v39, -v39, v42, v41
	v_div_fmas_f32 v39, v39, v40, v42
	v_div_fixup_f32 v38, v39, v38, 1.0
	v_pk_mul_f32 v[30:31], v[30:31], v[38:39] op_sel_hi:[1,0]
	v_pk_mul_f32 v[28:29], v[28:29], v[38:39] op_sel_hi:[1,0]
	v_pk_mul_f32 v[26:27], v[26:27], v[38:39] op_sel_hi:[1,0]
	v_pk_mul_f32 v[24:25], v[24:25], v[38:39] op_sel_hi:[1,0]
	v_pk_mul_f32 v[18:19], v[18:19], v[38:39] op_sel_hi:[1,0]
	v_pk_mul_f32 v[16:17], v[16:17], v[38:39] op_sel_hi:[1,0]
	v_pk_mul_f32 v[22:23], v[22:23], v[38:39] op_sel_hi:[1,0]
	v_pk_mul_f32 v[20:21], v[20:21], v[38:39] op_sel_hi:[1,0]
	v_max_f32_e32 v28, 0, v28
	v_max_f32_e32 v24, 0, v24
	v_max_f32_e32 v29, 0, v29
	v_max_f32_e32 v25, 0, v25
	v_max_f32_e32 v30, 0, v30
	v_max_f32_e32 v26, 0, v26
	v_max_f32_e32 v31, 0, v31
	v_max_f32_e32 v27, 0, v27
	v_max_f32_e32 v16, 0, v16
	v_max_f32_e32 v17, 0, v17
	v_max_f32_e32 v18, 0, v18
	v_max_f32_e32 v19, 0, v19
	v_max_f32_e32 v20, 0, v20
	v_max_f32_e32 v21, 0, v21
	v_max_f32_e32 v22, 0, v22
	v_max_f32_e32 v23, 0, v23
	v_mul_f32_e32 v28, v28, v28
	v_mul_f32_e32 v24, v24, v24
	v_mul_f32_e32 v29, v29, v29
	v_mul_f32_e32 v25, v25, v25
	v_mul_f32_e32 v30, v30, v30
	v_mul_f32_e32 v26, v26, v26
	v_mul_f32_e32 v31, v31, v31
	v_mul_f32_e32 v27, v27, v27
	v_mul_f32_e32 v38, v16, v16
	v_mul_f32_e32 v39, v17, v17
	v_mul_f32_e32 v40, v18, v18
	v_mul_f32_e32 v41, v19, v19
	v_cvt_pk_bf16_f32 v16, v28, v29
	v_cvt_pk_bf16_f32 v17, v30, v31
	v_cvt_pk_bf16_f32 v18, v24, v25
	v_cvt_pk_bf16_f32 v19, v26, v27
	v_mul_f32_e32 v20, v20, v20
	v_mul_f32_e32 v21, v21, v21
	v_mul_f32_e32 v22, v22, v22
	v_mul_f32_e32 v23, v23, v23
	global_store_dwordx4 v[34:35], v[16:19], off nt
	s_nop 1
	v_cvt_pk_bf16_f32 v16, v20, v21
	v_cvt_pk_bf16_f32 v17, v22, v23
	v_cvt_pk_bf16_f32 v18, v38, v39
	v_cvt_pk_bf16_f32 v19, v40, v41
	global_store_dwordx4 v[34:35], v[16:19], off offset:256 nt
	s_nop 1
	v_mov_b32_e32 v16, v187
	v_fmamk_f32 v16, v16, 0x3a000000, v154
	v_mul_f32_e32 v17, 0x4f800000, v16
	v_cmp_gt_f32_e32 vcc, s70, v16
	s_nop 1
	v_cndmask_b32_e32 v18, v16, v17, vcc
	v_sqrt_f32_e32 v19, v18
	v_lshlrev_b64 v[16:17], 14, v[32:33]
	v_lshl_add_u64 v[16:17], s[12:13], 0, v[16:17]
	v_lshl_add_u64 v[16:17], v[16:17], 0, v[144:145]
	v_add_u32_e32 v20, -1, v19
	v_add_u32_e32 v21, 1, v19
	v_fma_f32 v22, -v20, v19, v18
	v_fma_f32 v23, -v21, v19, v18
	v_cmp_ge_f32_e64 s[0:1], 0, v22
	s_nop 1
	v_cndmask_b32_e64 v19, v19, v20, s[0:1]
	v_cmp_lt_f32_e64 s[0:1], 0, v23
	s_nop 1
	v_cndmask_b32_e64 v19, v19, v21, s[0:1]
	v_mul_f32_e32 v20, 0x37800000, v19
	v_cndmask_b32_e32 v19, v19, v20, vcc
	v_cmp_class_f32_e32 vcc, v18, v155
	s_nop 1
	v_cndmask_b32_e32 v18, v19, v18, vcc
	v_div_scale_f32 v19, s[0:1], v18, v18, 1.0
	v_rcp_f32_e32 v20, v19
	v_div_scale_f32 v21, vcc, 1.0, v18, 1.0
	s_mov_b64 s[0:1], -1
	v_fma_f32 v22, -v19, v20, 1.0
	v_fmac_f32_e32 v20, v22, v20
	v_mul_f32_e32 v22, v21, v20
	v_fma_f32 v23, -v19, v22, v21
	v_fmac_f32_e32 v22, v23, v20
	v_fma_f32 v19, -v19, v22, v21
	v_div_fmas_f32 v19, v19, v20, v22
	v_div_fixup_f32 v18, v19, v18, 1.0
	v_pk_mul_f32 v[14:15], v[14:15], v[18:19] op_sel_hi:[1,0]
	v_pk_mul_f32 v[12:13], v[12:13], v[18:19] op_sel_hi:[1,0]
	v_pk_mul_f32 v[10:11], v[10:11], v[18:19] op_sel_hi:[1,0]
	v_pk_mul_f32 v[8:9], v[8:9], v[18:19] op_sel_hi:[1,0]
	v_pk_mul_f32 v[2:3], v[2:3], v[18:19] op_sel_hi:[1,0]
	v_pk_mul_f32 v[0:1], v[0:1], v[18:19] op_sel_hi:[1,0]
	v_pk_mul_f32 v[6:7], v[6:7], v[18:19] op_sel_hi:[1,0]
	v_pk_mul_f32 v[4:5], v[4:5], v[18:19] op_sel_hi:[1,0]
	v_max_f32_e32 v12, 0, v12
	v_max_f32_e32 v8, 0, v8
	v_max_f32_e32 v13, 0, v13
	v_max_f32_e32 v9, 0, v9
	v_max_f32_e32 v14, 0, v14
	v_max_f32_e32 v10, 0, v10
	v_max_f32_e32 v15, 0, v15
	v_max_f32_e32 v11, 0, v11
	v_max_f32_e32 v0, 0, v0
	v_max_f32_e32 v1, 0, v1
	v_max_f32_e32 v2, 0, v2
	v_max_f32_e32 v3, 0, v3
	s_andn2_b64 vcc, exec, s[6:7]
	v_max_f32_e32 v4, 0, v4
	v_max_f32_e32 v5, 0, v5
	v_max_f32_e32 v6, 0, v6
	v_max_f32_e32 v7, 0, v7
	v_mul_f32_e32 v12, v12, v12
	v_mul_f32_e32 v8, v8, v8
	v_mul_f32_e32 v13, v13, v13
	v_mul_f32_e32 v9, v9, v9
	v_mul_f32_e32 v14, v14, v14
	v_mul_f32_e32 v10, v10, v10
	v_mul_f32_e32 v15, v15, v15
	v_mul_f32_e32 v11, v11, v11
	v_mul_f32_e32 v18, v0, v0
	v_mul_f32_e32 v19, v1, v1
	v_mul_f32_e32 v20, v2, v2
	v_mul_f32_e32 v21, v3, v3
	v_cvt_pk_bf16_f32 v0, v12, v13
	v_cvt_pk_bf16_f32 v1, v14, v15
	v_cvt_pk_bf16_f32 v2, v8, v9
	v_cvt_pk_bf16_f32 v3, v10, v11
	v_mul_f32_e32 v4, v4, v4
	v_mul_f32_e32 v5, v5, v5
	v_mul_f32_e32 v6, v6, v6
	v_mul_f32_e32 v7, v7, v7
	global_store_dwordx4 v[16:17], v[0:3], off nt
	s_nop 1
	v_cvt_pk_bf16_f32 v0, v4, v5
	v_cvt_pk_bf16_f32 v1, v6, v7
	v_cvt_pk_bf16_f32 v2, v18, v19
	v_cvt_pk_bf16_f32 v3, v20, v21
	global_store_dwordx4 v[16:17], v[0:3], off offset:256 nt
	s_cbranch_vccnz .LBB0_724
	s_andn2_b64 vcc, exec, s[10:11]
	s_cbranch_vccnz .LBB0_723
	s_barrier
	s_branch .LBB0_723

.LBB0_899:
	v_lshl_or_b32 v150, s0, 8, v159
	v_ashrrev_i32_e32 v151, 31, v150
	v_lshl_add_u64 v[152:153], v[150:151], 2, s[14:15]
	global_load_dword v136, v[152:153], off
	global_load_dword v181, v[152:153], off offset:64
	global_load_dword v182, v[152:153], off offset:128
	global_load_dword v183, v[152:153], off offset:192
	global_load_dword v184, v[152:153], off offset:512
	global_load_dword v185, v[152:153], off offset:576
	global_load_dword v186, v[152:153], off offset:640
	global_load_dword v187, v[152:153], off offset:704
	s_cmp_lt_i32 s8, 24
	s_cselect_b64 s[60:61], -1, 0
	s_lshr_b32 s1, s8, 2
	s_and_b32 s1, s1, 0xffffffe
	s_ashr_i32 s0, s0, 6
	s_lshl_b32 s8, s8, 1
	s_add_i32 s0, s0, s1
	s_and_b32 s8, s8, 14
	s_lshl_b32 s0, s0, 4
	s_or_b32 s58, s0, s8
	s_waitcnt vmcnt(0)
	v_fmamk_f32 v136, v136, 0x3a000000, v163
	v_cmp_gt_f32_e32 vcc, s74, v136
	v_mul_f32_e32 v152, 0x4f800000, v136
	s_nop 0
	v_cndmask_b32_e32 v136, v136, v152, vcc
	v_sqrt_f32_e32 v152, v136
	s_nop 0
	v_add_u32_e32 v153, -1, v152
	v_fma_f32 v154, -v153, v152, v136
	v_cmp_ge_f32_e64 s[0:1], 0, v154
	v_add_u32_e32 v154, 1, v152
	s_nop 0
	v_cndmask_b32_e64 v153, v152, v153, s[0:1]
	v_fma_f32 v152, -v154, v152, v136
	v_cmp_lt_f32_e64 s[0:1], 0, v152
	s_nop 1
	v_cndmask_b32_e64 v152, v153, v154, s[0:1]
	v_mul_f32_e32 v153, 0x37800000, v152
	v_cndmask_b32_e32 v152, v152, v153, vcc
	v_cmp_class_f32_e32 vcc, v136, v164
	s_nop 1
	v_cndmask_b32_e32 v136, v152, v136, vcc
	v_div_scale_f32 v152, s[0:1], v136, v136, 1.0
	v_rcp_f32_e32 v153, v152
	s_mov_b64 s[0:1], -1
	v_fma_f32 v154, -v152, v153, 1.0
	v_fmac_f32_e32 v153, v154, v153
	v_div_scale_f32 v154, vcc, 1.0, v136, 1.0
	v_mul_f32_e32 v155, v154, v153
	v_fma_f32 v165, -v152, v155, v154
	v_fmac_f32_e32 v155, v165, v153
	v_fma_f32 v152, -v152, v155, v154
	v_div_fmas_f32 v152, v152, v153, v155
	v_div_fixup_f32 v154, v152, v136, 1.0
	v_lshlrev_b32_e32 v136, 7, v150
	v_and_b32_e32 v136, 0x1fa780, v136
	v_pk_mul_f32 v[126:127], v[126:127], v[154:155] op_sel_hi:[1,0]
	v_pk_mul_f32 v[124:125], v[124:125], v[154:155] op_sel_hi:[1,0]
	v_pk_mul_f32 v[122:123], v[122:123], v[154:155] op_sel_hi:[1,0]
	v_pk_mul_f32 v[120:121], v[120:121], v[154:155] op_sel_hi:[1,0]
	s_and_b64 vcc, exec, s[60:61]
	v_lshlrev_b32_e32 v136, 1, v136
	v_lshlrev_b32_e32 v152, 1, v138
	s_cbranch_vccnz .LBB0_931
	s_andn2_b64 vcc, exec, s[0:1]
	s_cbranch_vccz .LBB0_932

.LBB0_903:
	s_nop 1
	v_or_b32_e32 v112, 16, v150
	v_ashrrev_i32_e32 v113, 31, v112
	v_lshl_add_u64 v[114:115], v[112:113], 2, s[14:15]
	s_nop 1
	v_mov_b32_e32 v114, v181
	v_lshlrev_b32_e32 v116, 7, v112
	v_and_b32_e32 v116, 0x1fef80, v116
	s_mov_b64 s[60:61], -1
	v_lshlrev_b32_e32 v136, 1, v116
	v_fmamk_f32 v114, v114, 0x3a000000, v163
	v_mul_f32_e32 v115, 0x4f800000, v114
	v_cmp_gt_f32_e32 vcc, s74, v114
	s_nop 1
	v_cndmask_b32_e32 v114, v114, v115, vcc
	v_sqrt_f32_e32 v115, v114
	s_nop 0
	v_add_u32_e32 v117, -1, v115
	v_add_u32_e32 v118, 1, v115
	v_fma_f32 v119, -v117, v115, v114
	v_fma_f32 v120, -v118, v115, v114
	v_cmp_ge_f32_e64 s[0:1], 0, v119
	s_nop 1
	v_cndmask_b32_e64 v115, v115, v117, s[0:1]
	v_cmp_lt_f32_e64 s[0:1], 0, v120
	s_nop 1
	v_cndmask_b32_e64 v115, v115, v118, s[0:1]
	v_mul_f32_e32 v117, 0x37800000, v115
	v_cndmask_b32_e32 v115, v115, v117, vcc
	v_cmp_class_f32_e32 vcc, v114, v164
	s_nop 1
	v_cndmask_b32_e32 v114, v115, v114, vcc
	v_div_scale_f32 v115, s[0:1], v114, v114, 1.0
	v_rcp_f32_e32 v117, v115
	v_div_scale_f32 v118, vcc, 1.0, v114, 1.0
	v_fma_f32 v119, -v115, v117, 1.0
	v_fmac_f32_e32 v117, v119, v117
	v_mul_f32_e32 v119, v118, v117
	v_fma_f32 v120, -v115, v119, v118
	v_fmac_f32_e32 v119, v120, v117
	v_fma_f32 v115, -v115, v119, v118
	v_div_fmas_f32 v115, v115, v117, v119
	v_div_fixup_f32 v114, v115, v114, 1.0
	s_and_b64 vcc, exec, s[8:9]
	v_pk_mul_f32 v[110:111], v[110:111], v[114:115] op_sel_hi:[1,0]
	v_pk_mul_f32 v[108:109], v[108:109], v[114:115] op_sel_hi:[1,0]
	v_pk_mul_f32 v[106:107], v[106:107], v[114:115] op_sel_hi:[1,0]
	v_pk_mul_f32 v[104:105], v[104:105], v[114:115] op_sel_hi:[1,0]
	s_cbranch_vccz .LBB0_935
	s_andn2_b64 vcc, exec, s[60:61]
	s_cbranch_vccz .LBB0_936

.LBB0_907:
	s_nop 1
	v_or_b32_e32 v96, 32, v150
	v_ashrrev_i32_e32 v97, 31, v96
	v_lshl_add_u64 v[98:99], v[96:97], 2, s[14:15]
	s_nop 1
	v_mov_b32_e32 v98, v182
	v_lshlrev_b32_e32 v100, 7, v96
	v_and_b32_e32 v100, 0x1ff780, v100
	s_mov_b64 s[60:61], -1
	v_lshlrev_b32_e32 v136, 1, v100
	v_fmamk_f32 v98, v98, 0x3a000000, v163
	v_mul_f32_e32 v99, 0x4f800000, v98
	v_cmp_gt_f32_e32 vcc, s74, v98
	s_nop 1
	v_cndmask_b32_e32 v98, v98, v99, vcc
	v_sqrt_f32_e32 v99, v98
	s_nop 0
	v_add_u32_e32 v101, -1, v99
	v_add_u32_e32 v102, 1, v99
	v_fma_f32 v103, -v101, v99, v98
	v_fma_f32 v104, -v102, v99, v98
	v_cmp_ge_f32_e64 s[0:1], 0, v103
	s_nop 1
	v_cndmask_b32_e64 v99, v99, v101, s[0:1]
	v_cmp_lt_f32_e64 s[0:1], 0, v104
	s_nop 1
	v_cndmask_b32_e64 v99, v99, v102, s[0:1]
	v_mul_f32_e32 v101, 0x37800000, v99
	v_cndmask_b32_e32 v99, v99, v101, vcc
	v_cmp_class_f32_e32 vcc, v98, v164
	s_nop 1
	v_cndmask_b32_e32 v98, v99, v98, vcc
	v_div_scale_f32 v99, s[0:1], v98, v98, 1.0
	v_rcp_f32_e32 v101, v99
	v_div_scale_f32 v102, vcc, 1.0, v98, 1.0
	v_fma_f32 v103, -v99, v101, 1.0
	v_fmac_f32_e32 v101, v103, v101
	v_mul_f32_e32 v103, v102, v101
	v_fma_f32 v104, -v99, v103, v102
	v_fmac_f32_e32 v103, v104, v101
	v_fma_f32 v99, -v99, v103, v102
	v_div_fmas_f32 v99, v99, v101, v103
	v_div_fixup_f32 v98, v99, v98, 1.0
	s_and_b64 vcc, exec, s[8:9]
	v_pk_mul_f32 v[94:95], v[94:95], v[98:99] op_sel_hi:[1,0]
	v_pk_mul_f32 v[92:93], v[92:93], v[98:99] op_sel_hi:[1,0]
	v_pk_mul_f32 v[90:91], v[90:91], v[98:99] op_sel_hi:[1,0]
	v_pk_mul_f32 v[88:89], v[88:89], v[98:99] op_sel_hi:[1,0]
	s_cbranch_vccz .LBB0_939
	s_andn2_b64 vcc, exec, s[60:61]
	s_cbranch_vccz .LBB0_940

.LBB0_911:
	s_nop 1
	v_or_b32_e32 v80, 48, v150
	v_ashrrev_i32_e32 v81, 31, v80
	v_lshl_add_u64 v[82:83], v[80:81], 2, s[14:15]
	s_nop 1
	v_mov_b32_e32 v82, v183
	v_lshlrev_b32_e32 v84, 7, v80
	v_and_b32_e32 v84, 0x1fff80, v84
	s_mov_b64 s[60:61], -1
	v_lshlrev_b32_e32 v136, 1, v84
	v_fmamk_f32 v82, v82, 0x3a000000, v163
	v_mul_f32_e32 v83, 0x4f800000, v82
	v_cmp_gt_f32_e32 vcc, s74, v82
	s_nop 1
	v_cndmask_b32_e32 v82, v82, v83, vcc
	v_sqrt_f32_e32 v83, v82
	s_nop 0
	v_add_u32_e32 v85, -1, v83
	v_add_u32_e32 v86, 1, v83
	v_fma_f32 v87, -v85, v83, v82
	v_fma_f32 v88, -v86, v83, v82
	v_cmp_ge_f32_e64 s[0:1], 0, v87
	s_nop 1
	v_cndmask_b32_e64 v83, v83, v85, s[0:1]
	v_cmp_lt_f32_e64 s[0:1], 0, v88
	s_nop 1
	v_cndmask_b32_e64 v83, v83, v86, s[0:1]
	v_mul_f32_e32 v85, 0x37800000, v83
	v_cndmask_b32_e32 v83, v83, v85, vcc
	v_cmp_class_f32_e32 vcc, v82, v164
	s_nop 1
	v_cndmask_b32_e32 v82, v83, v82, vcc
	v_div_scale_f32 v83, s[0:1], v82, v82, 1.0
	v_rcp_f32_e32 v85, v83
	v_div_scale_f32 v86, vcc, 1.0, v82, 1.0
	v_fma_f32 v87, -v83, v85, 1.0
	v_fmac_f32_e32 v85, v87, v85
	v_mul_f32_e32 v87, v86, v85
	v_fma_f32 v88, -v83, v87, v86
	v_fmac_f32_e32 v87, v88, v85
	v_fma_f32 v83, -v83, v87, v86
	v_div_fmas_f32 v83, v83, v85, v87
	v_div_fixup_f32 v82, v83, v82, 1.0
	s_and_b64 vcc, exec, s[8:9]
	v_pk_mul_f32 v[78:79], v[78:79], v[82:83] op_sel_hi:[1,0]
	v_pk_mul_f32 v[76:77], v[76:77], v[82:83] op_sel_hi:[1,0]
	v_pk_mul_f32 v[74:75], v[74:75], v[82:83] op_sel_hi:[1,0]
	v_pk_mul_f32 v[72:73], v[72:73], v[82:83] op_sel_hi:[1,0]
	s_cbranch_vccz .LBB0_943
	s_andn2_b64 vcc, exec, s[60:61]
	s_cbranch_vccz .LBB0_944

.LBB0_915:
	s_nop 1
	v_or_b32_e32 v64, 0x80, v150
	v_ashrrev_i32_e32 v65, 31, v64
	v_lshl_add_u64 v[66:67], v[64:65], 2, s[14:15]
	s_nop 1
	v_mov_b32_e32 v66, v184
	v_lshlrev_b32_e32 v68, 7, v64
	v_and_b32_e32 v68, 0x1fe780, v68
	s_mov_b64 s[60:61], -1
	v_lshlrev_b32_e32 v136, 1, v68
	v_fmamk_f32 v66, v66, 0x3a000000, v163
	v_mul_f32_e32 v67, 0x4f800000, v66
	v_cmp_gt_f32_e32 vcc, s74, v66
	s_nop 1
	v_cndmask_b32_e32 v66, v66, v67, vcc
	v_sqrt_f32_e32 v67, v66
	s_nop 0
	v_add_u32_e32 v69, -1, v67
	v_add_u32_e32 v70, 1, v67
	v_fma_f32 v71, -v69, v67, v66
	v_fma_f32 v72, -v70, v67, v66
	v_cmp_ge_f32_e64 s[0:1], 0, v71
	s_nop 1
	v_cndmask_b32_e64 v67, v67, v69, s[0:1]
	v_cmp_lt_f32_e64 s[0:1], 0, v72
	s_nop 1
	v_cndmask_b32_e64 v67, v67, v70, s[0:1]
	v_mul_f32_e32 v69, 0x37800000, v67
	v_cndmask_b32_e32 v67, v67, v69, vcc
	v_cmp_class_f32_e32 vcc, v66, v164
	s_nop 1
	v_cndmask_b32_e32 v66, v67, v66, vcc
	v_div_scale_f32 v67, s[0:1], v66, v66, 1.0
	v_rcp_f32_e32 v69, v67
	v_div_scale_f32 v70, vcc, 1.0, v66, 1.0
	v_fma_f32 v71, -v67, v69, 1.0
	v_fmac_f32_e32 v69, v71, v69
	v_mul_f32_e32 v71, v70, v69
	v_fma_f32 v72, -v67, v71, v70
	v_fmac_f32_e32 v71, v72, v69
	v_fma_f32 v67, -v67, v71, v70
	v_div_fmas_f32 v67, v67, v69, v71
	v_div_fixup_f32 v66, v67, v66, 1.0
	s_and_b64 vcc, exec, s[8:9]
	v_pk_mul_f32 v[62:63], v[62:63], v[66:67] op_sel_hi:[1,0]
	v_pk_mul_f32 v[60:61], v[60:61], v[66:67] op_sel_hi:[1,0]
	v_pk_mul_f32 v[58:59], v[58:59], v[66:67] op_sel_hi:[1,0]
	v_pk_mul_f32 v[56:57], v[56:57], v[66:67] op_sel_hi:[1,0]
	s_cbranch_vccz .LBB0_947
	s_andn2_b64 vcc, exec, s[60:61]
	s_cbranch_vccz .LBB0_948

.LBB0_919:
	s_nop 1
	v_or_b32_e32 v48, 0x90, v150
	v_ashrrev_i32_e32 v49, 31, v48
	v_lshl_add_u64 v[50:51], v[48:49], 2, s[14:15]
	s_nop 1
	v_mov_b32_e32 v50, v185
	v_lshlrev_b32_e32 v52, 7, v48
	v_and_b32_e32 v52, 0x1fef80, v52
	s_mov_b64 s[60:61], -1
	v_lshlrev_b32_e32 v136, 1, v52
	v_fmamk_f32 v50, v50, 0x3a000000, v163
	v_mul_f32_e32 v51, 0x4f800000, v50
	v_cmp_gt_f32_e32 vcc, s74, v50
	s_nop 1
	v_cndmask_b32_e32 v50, v50, v51, vcc
	v_sqrt_f32_e32 v51, v50
	s_nop 0
	v_add_u32_e32 v53, -1, v51
	v_add_u32_e32 v54, 1, v51
	v_fma_f32 v55, -v53, v51, v50
	v_fma_f32 v56, -v54, v51, v50
	v_cmp_ge_f32_e64 s[0:1], 0, v55
	s_nop 1
	v_cndmask_b32_e64 v51, v51, v53, s[0:1]
	v_cmp_lt_f32_e64 s[0:1], 0, v56
	s_nop 1
	v_cndmask_b32_e64 v51, v51, v54, s[0:1]
	v_mul_f32_e32 v53, 0x37800000, v51
	v_cndmask_b32_e32 v51, v51, v53, vcc
	v_cmp_class_f32_e32 vcc, v50, v164
	s_nop 1
	v_cndmask_b32_e32 v50, v51, v50, vcc
	v_div_scale_f32 v51, s[0:1], v50, v50, 1.0
	v_rcp_f32_e32 v53, v51
	v_div_scale_f32 v54, vcc, 1.0, v50, 1.0
	v_fma_f32 v55, -v51, v53, 1.0
	v_fmac_f32_e32 v53, v55, v53
	v_mul_f32_e32 v55, v54, v53
	v_fma_f32 v56, -v51, v55, v54
	v_fmac_f32_e32 v55, v56, v53
	v_fma_f32 v51, -v51, v55, v54
	v_div_fmas_f32 v51, v51, v53, v55
	v_div_fixup_f32 v50, v51, v50, 1.0
	s_and_b64 vcc, exec, s[8:9]
	v_pk_mul_f32 v[46:47], v[46:47], v[50:51] op_sel_hi:[1,0]
	v_pk_mul_f32 v[44:45], v[44:45], v[50:51] op_sel_hi:[1,0]
	v_pk_mul_f32 v[42:43], v[42:43], v[50:51] op_sel_hi:[1,0]
	v_pk_mul_f32 v[40:41], v[40:41], v[50:51] op_sel_hi:[1,0]
	s_cbranch_vccz .LBB0_951
	s_andn2_b64 vcc, exec, s[60:61]
	s_cbranch_vccz .LBB0_952

.LBB0_923:
	s_nop 1
	v_or_b32_e32 v32, 0xa0, v150
	v_ashrrev_i32_e32 v33, 31, v32
	v_lshl_add_u64 v[34:35], v[32:33], 2, s[14:15]
	s_nop 1
	v_mov_b32_e32 v34, v186
	v_lshlrev_b32_e32 v36, 7, v32
	v_and_b32_e32 v36, 0x1ff780, v36
	s_mov_b64 s[60:61], -1
	v_lshlrev_b32_e32 v136, 1, v36
	v_fmamk_f32 v34, v34, 0x3a000000, v163
	v_mul_f32_e32 v35, 0x4f800000, v34
	v_cmp_gt_f32_e32 vcc, s74, v34
	s_nop 1
	v_cndmask_b32_e32 v34, v34, v35, vcc
	v_sqrt_f32_e32 v35, v34
	s_nop 0
	v_add_u32_e32 v37, -1, v35
	v_add_u32_e32 v38, 1, v35
	v_fma_f32 v39, -v37, v35, v34
	v_fma_f32 v40, -v38, v35, v34
	v_cmp_ge_f32_e64 s[0:1], 0, v39
	s_nop 1
	v_cndmask_b32_e64 v35, v35, v37, s[0:1]
	v_cmp_lt_f32_e64 s[0:1], 0, v40
	s_nop 1
	v_cndmask_b32_e64 v35, v35, v38, s[0:1]
	v_mul_f32_e32 v37, 0x37800000, v35
	v_cndmask_b32_e32 v35, v35, v37, vcc
	v_cmp_class_f32_e32 vcc, v34, v164
	s_nop 1
	v_cndmask_b32_e32 v34, v35, v34, vcc
	v_div_scale_f32 v35, s[0:1], v34, v34, 1.0
	v_rcp_f32_e32 v37, v35
	v_div_scale_f32 v38, vcc, 1.0, v34, 1.0
	v_fma_f32 v39, -v35, v37, 1.0
	v_fmac_f32_e32 v37, v39, v37
	v_mul_f32_e32 v39, v38, v37
	v_fma_f32 v40, -v35, v39, v38
	v_fmac_f32_e32 v39, v40, v37
	v_fma_f32 v35, -v35, v39, v38
	v_div_fmas_f32 v35, v35, v37, v39
	v_div_fixup_f32 v34, v35, v34, 1.0
	s_and_b64 vcc, exec, s[8:9]
	v_pk_mul_f32 v[30:31], v[30:31], v[34:35] op_sel_hi:[1,0]
	v_pk_mul_f32 v[28:29], v[28:29], v[34:35] op_sel_hi:[1,0]
	v_pk_mul_f32 v[26:27], v[26:27], v[34:35] op_sel_hi:[1,0]
	v_pk_mul_f32 v[24:25], v[24:25], v[34:35] op_sel_hi:[1,0]
	s_cbranch_vccz .LBB0_955
	s_andn2_b64 vcc, exec, s[60:61]
	s_cbranch_vccz .LBB0_956

.LBB0_927:
	s_nop 1
	v_or_b32_e32 v16, 0xb0, v150
	v_ashrrev_i32_e32 v17, 31, v16
	v_lshl_add_u64 v[18:19], v[16:17], 2, s[14:15]
	s_nop 1
	v_mov_b32_e32 v18, v187
	v_lshlrev_b32_e32 v20, 7, v16
	v_and_b32_e32 v20, 0x1fff80, v20
	s_mov_b64 s[60:61], -1
	v_lshlrev_b32_e32 v136, 1, v20
	v_fmamk_f32 v18, v18, 0x3a000000, v163
	v_mul_f32_e32 v19, 0x4f800000, v18
	v_cmp_gt_f32_e32 vcc, s74, v18
	s_nop 1
	v_cndmask_b32_e32 v18, v18, v19, vcc
	v_sqrt_f32_e32 v19, v18
	s_nop 0
	v_add_u32_e32 v21, -1, v19
	v_add_u32_e32 v22, 1, v19
	v_fma_f32 v23, -v21, v19, v18
	v_fma_f32 v24, -v22, v19, v18
	v_cmp_ge_f32_e64 s[0:1], 0, v23
	s_nop 1
	v_cndmask_b32_e64 v19, v19, v21, s[0:1]
	v_cmp_lt_f32_e64 s[0:1], 0, v24
	s_nop 1
	v_cndmask_b32_e64 v19, v19, v22, s[0:1]
	v_mul_f32_e32 v21, 0x37800000, v19
	v_cndmask_b32_e32 v19, v19, v21, vcc
	v_cmp_class_f32_e32 vcc, v18, v164
	s_nop 1
	v_cndmask_b32_e32 v18, v19, v18, vcc
	v_div_scale_f32 v19, s[0:1], v18, v18, 1.0
	v_rcp_f32_e32 v21, v19
	v_div_scale_f32 v22, vcc, 1.0, v18, 1.0
	v_fma_f32 v23, -v19, v21, 1.0
	v_fmac_f32_e32 v21, v23, v21
	v_mul_f32_e32 v23, v22, v21
	v_fma_f32 v24, -v19, v23, v22
	v_fmac_f32_e32 v23, v24, v21
	v_fma_f32 v19, -v19, v23, v22
	v_div_fmas_f32 v19, v19, v21, v23
	v_div_fixup_f32 v18, v19, v18, 1.0
	s_and_b64 vcc, exec, s[8:9]
	v_pk_mul_f32 v[14:15], v[14:15], v[18:19] op_sel_hi:[1,0]
	v_pk_mul_f32 v[12:13], v[12:13], v[18:19] op_sel_hi:[1,0]
	v_pk_mul_f32 v[10:11], v[10:11], v[18:19] op_sel_hi:[1,0]
	v_pk_mul_f32 v[8:9], v[8:9], v[18:19] op_sel_hi:[1,0]
	s_cbranch_vccz .LBB0_959
	s_andn2_b64 vcc, exec, s[60:61]
	s_cbranch_vccz .LBB0_960

.LBB0_1524:
	v_lshl_or_b32 v146, s0, 8, v149
	v_ashrrev_i32_e32 v147, 31, v146
	v_lshl_add_u64 v[144:145], v[146:147], 2, s[14:15]
	global_load_dword v157, v[144:145], off
	global_load_dword v181, v[144:145], off offset:64
	global_load_dword v182, v[144:145], off offset:128
	global_load_dword v183, v[144:145], off offset:192
	global_load_dword v184, v[144:145], off offset:512
	global_load_dword v185, v[144:145], off offset:576
	global_load_dword v186, v[144:145], off offset:640
	global_load_dword v187, v[144:145], off offset:704
	v_lshlrev_b64 v[158:159], 14, v[146:147]
	v_lshl_or_b32 v144, s1, 8, v150
	v_ashrrev_i32_e32 v145, 31, v144
	v_or_b32_e32 v156, 16, v146
	v_lshlrev_b64 v[144:145], 1, v[144:145]
	v_lshl_add_u64 v[158:159], s[12:13], 0, v[158:159]
	v_lshl_add_u64 v[158:159], v[158:159], 0, v[144:145]
	s_waitcnt vmcnt(0)
	v_fmamk_f32 v147, v157, 0x3a000000, v154
	v_mul_f32_e32 v157, 0x4f800000, v147
	v_cmp_gt_f32_e32 vcc, s62, v147
	s_nop 1
	v_cndmask_b32_e32 v147, v147, v157, vcc
	v_sqrt_f32_e32 v162, v147
	v_ashrrev_i32_e32 v157, 31, v156
	v_lshl_add_u64 v[160:161], v[156:157], 2, s[14:15]
	v_add_u32_e32 v163, -1, v162
	v_add_u32_e32 v164, 1, v162
	v_fma_f32 v165, -v163, v162, v147
	v_fma_f32 v166, -v164, v162, v147
	v_cmp_ge_f32_e64 s[0:1], 0, v165
	s_nop 1
	v_cndmask_b32_e64 v162, v162, v163, s[0:1]
	v_cmp_lt_f32_e64 s[0:1], 0, v166
	s_nop 1
	v_cndmask_b32_e64 v162, v162, v164, s[0:1]
	v_mul_f32_e32 v163, 0x37800000, v162
	v_cndmask_b32_e32 v162, v162, v163, vcc
	v_cmp_class_f32_e32 vcc, v147, v155
	s_nop 1
	v_cndmask_b32_e32 v147, v162, v147, vcc
	v_div_scale_f32 v162, s[0:1], v147, v147, 1.0
	v_rcp_f32_e32 v163, v162
	v_div_scale_f32 v164, vcc, 1.0, v147, 1.0
	v_fma_f32 v165, -v162, v163, 1.0
	v_fmac_f32_e32 v163, v165, v163
	v_mul_f32_e32 v165, v164, v163
	v_fma_f32 v166, -v162, v165, v164
	v_fmac_f32_e32 v165, v166, v163
	v_fma_f32 v162, -v162, v165, v164
	v_div_fmas_f32 v162, v162, v163, v165
	v_div_fixup_f32 v162, v162, v147, 1.0
	v_pk_mul_f32 v[126:127], v[126:127], v[162:163] op_sel_hi:[1,0]
	v_pk_mul_f32 v[124:125], v[124:125], v[162:163] op_sel_hi:[1,0]
	v_pk_mul_f32 v[122:123], v[122:123], v[162:163] op_sel_hi:[1,0]
	v_pk_mul_f32 v[120:121], v[120:121], v[162:163] op_sel_hi:[1,0]
	v_pk_mul_f32 v[114:115], v[114:115], v[162:163] op_sel_hi:[1,0]
	v_pk_mul_f32 v[112:113], v[112:113], v[162:163] op_sel_hi:[1,0]
	v_pk_mul_f32 v[118:119], v[118:119], v[162:163] op_sel_hi:[1,0]
	v_pk_mul_f32 v[116:117], v[116:117], v[162:163] op_sel_hi:[1,0]
	v_max_f32_e32 v124, 0, v124
	v_max_f32_e32 v120, 0, v120
	v_max_f32_e32 v125, 0, v125
	v_max_f32_e32 v121, 0, v121
	v_max_f32_e32 v126, 0, v126
	v_max_f32_e32 v122, 0, v122
	v_max_f32_e32 v127, 0, v127
	v_max_f32_e32 v123, 0, v123
	v_max_f32_e32 v112, 0, v112
	v_max_f32_e32 v113, 0, v113
	v_max_f32_e32 v114, 0, v114
	v_max_f32_e32 v115, 0, v115
	v_max_f32_e32 v116, 0, v116
	v_max_f32_e32 v117, 0, v117
	v_max_f32_e32 v118, 0, v118
	v_max_f32_e32 v119, 0, v119
	v_mul_f32_e32 v124, v124, v124
	v_mul_f32_e32 v120, v120, v120
	v_mul_f32_e32 v125, v125, v125
	v_mul_f32_e32 v121, v121, v121
	v_mul_f32_e32 v126, v126, v126
	v_mul_f32_e32 v122, v122, v122
	v_mul_f32_e32 v127, v127, v127
	v_mul_f32_e32 v123, v123, v123
	v_mul_f32_e32 v147, v112, v112
	v_mul_f32_e32 v162, v113, v113
	v_mul_f32_e32 v163, v114, v114
	v_mul_f32_e32 v164, v115, v115
	v_cvt_pk_bf16_f32 v112, v124, v125
	v_cvt_pk_bf16_f32 v113, v126, v127
	v_cvt_pk_bf16_f32 v114, v120, v121
	v_cvt_pk_bf16_f32 v115, v122, v123
	v_mul_f32_e32 v116, v116, v116
	v_mul_f32_e32 v117, v117, v117
	v_mul_f32_e32 v118, v118, v118
	v_mul_f32_e32 v119, v119, v119
	global_store_dwordx4 v[158:159], v[112:115], off nt
	s_nop 1
	v_cvt_pk_bf16_f32 v112, v116, v117
	v_cvt_pk_bf16_f32 v113, v118, v119
	v_cvt_pk_bf16_f32 v114, v147, v162
	v_cvt_pk_bf16_f32 v115, v163, v164
	global_store_dwordx4 v[158:159], v[112:115], off offset:256 nt
	s_nop 1
	v_mov_b32_e32 v114, v181
	s_nop 0
	v_or_b32_e32 v112, 32, v146
	v_ashrrev_i32_e32 v113, 31, v112
	v_lshl_add_u64 v[116:117], v[112:113], 2, s[14:15]
	v_fmamk_f32 v114, v114, 0x3a000000, v154
	v_mul_f32_e32 v115, 0x4f800000, v114
	v_cmp_gt_f32_e32 vcc, s62, v114
	s_nop 1
	v_cndmask_b32_e32 v118, v114, v115, vcc
	v_sqrt_f32_e32 v119, v118
	v_lshlrev_b64 v[114:115], 14, v[156:157]
	v_lshl_add_u64 v[114:115], s[12:13], 0, v[114:115]
	v_lshl_add_u64 v[114:115], v[114:115], 0, v[144:145]
	v_add_u32_e32 v120, -1, v119
	v_add_u32_e32 v121, 1, v119
	v_fma_f32 v122, -v120, v119, v118
	v_fma_f32 v123, -v121, v119, v118
	v_cmp_ge_f32_e64 s[0:1], 0, v122
	s_nop 1
	v_cndmask_b32_e64 v119, v119, v120, s[0:1]
	v_cmp_lt_f32_e64 s[0:1], 0, v123
	s_nop 1
	v_cndmask_b32_e64 v119, v119, v121, s[0:1]
	v_mul_f32_e32 v120, 0x37800000, v119
	v_cndmask_b32_e32 v119, v119, v120, vcc
	v_cmp_class_f32_e32 vcc, v118, v155
	s_nop 1
	v_cndmask_b32_e32 v118, v119, v118, vcc
	v_div_scale_f32 v119, s[0:1], v118, v118, 1.0
	v_rcp_f32_e32 v120, v119
	v_div_scale_f32 v121, vcc, 1.0, v118, 1.0
	v_fma_f32 v122, -v119, v120, 1.0
	v_fmac_f32_e32 v120, v122, v120
	v_mul_f32_e32 v122, v121, v120
	v_fma_f32 v123, -v119, v122, v121
	v_fmac_f32_e32 v122, v123, v120
	v_fma_f32 v119, -v119, v122, v121
	v_div_fmas_f32 v119, v119, v120, v122
	v_div_fixup_f32 v118, v119, v118, 1.0
	v_pk_mul_f32 v[110:111], v[110:111], v[118:119] op_sel_hi:[1,0]
	v_pk_mul_f32 v[108:109], v[108:109], v[118:119] op_sel_hi:[1,0]
	v_pk_mul_f32 v[106:107], v[106:107], v[118:119] op_sel_hi:[1,0]
	v_pk_mul_f32 v[104:105], v[104:105], v[118:119] op_sel_hi:[1,0]
	v_pk_mul_f32 v[98:99], v[98:99], v[118:119] op_sel_hi:[1,0]
	v_pk_mul_f32 v[96:97], v[96:97], v[118:119] op_sel_hi:[1,0]
	v_pk_mul_f32 v[102:103], v[102:103], v[118:119] op_sel_hi:[1,0]
	v_pk_mul_f32 v[100:101], v[100:101], v[118:119] op_sel_hi:[1,0]
	v_max_f32_e32 v108, 0, v108
	v_max_f32_e32 v104, 0, v104
	v_max_f32_e32 v109, 0, v109
	v_max_f32_e32 v105, 0, v105
	v_max_f32_e32 v110, 0, v110
	v_max_f32_e32 v106, 0, v106
	v_max_f32_e32 v111, 0, v111
	v_max_f32_e32 v107, 0, v107
	v_max_f32_e32 v96, 0, v96
	v_max_f32_e32 v97, 0, v97
	v_max_f32_e32 v98, 0, v98
	v_max_f32_e32 v99, 0, v99
	v_max_f32_e32 v100, 0, v100
	v_max_f32_e32 v101, 0, v101
	v_max_f32_e32 v102, 0, v102
	v_max_f32_e32 v103, 0, v103
	v_mul_f32_e32 v108, v108, v108
	v_mul_f32_e32 v104, v104, v104
	v_mul_f32_e32 v109, v109, v109
	v_mul_f32_e32 v105, v105, v105
	v_mul_f32_e32 v110, v110, v110
	v_mul_f32_e32 v106, v106, v106
	v_mul_f32_e32 v111, v111, v111
	v_mul_f32_e32 v107, v107, v107
	v_mul_f32_e32 v118, v96, v96
	v_mul_f32_e32 v119, v97, v97
	v_mul_f32_e32 v120, v98, v98
	v_mul_f32_e32 v121, v99, v99
	v_cvt_pk_bf16_f32 v96, v108, v109
	v_cvt_pk_bf16_f32 v97, v110, v111
	v_cvt_pk_bf16_f32 v98, v104, v105
	v_cvt_pk_bf16_f32 v99, v106, v107
	v_mul_f32_e32 v100, v100, v100
	v_mul_f32_e32 v101, v101, v101
	v_mul_f32_e32 v102, v102, v102
	v_mul_f32_e32 v103, v103, v103
	global_store_dwordx4 v[114:115], v[96:99], off nt
	s_nop 1
	v_cvt_pk_bf16_f32 v96, v100, v101
	v_cvt_pk_bf16_f32 v97, v102, v103
	v_cvt_pk_bf16_f32 v98, v118, v119
	v_cvt_pk_bf16_f32 v99, v120, v121
	global_store_dwordx4 v[114:115], v[96:99], off offset:256 nt
	s_nop 1
	v_mov_b32_e32 v98, v182
	s_nop 0
	v_or_b32_e32 v96, 48, v146
	v_ashrrev_i32_e32 v97, 31, v96
	v_lshl_add_u64 v[100:101], v[96:97], 2, s[14:15]
	v_fmamk_f32 v98, v98, 0x3a000000, v154
	v_mul_f32_e32 v99, 0x4f800000, v98
	v_cmp_gt_f32_e32 vcc, s62, v98
	s_nop 1
	v_cndmask_b32_e32 v102, v98, v99, vcc
	v_sqrt_f32_e32 v103, v102
	v_lshlrev_b64 v[98:99], 14, v[112:113]
	v_lshl_add_u64 v[98:99], s[12:13], 0, v[98:99]
	v_lshl_add_u64 v[98:99], v[98:99], 0, v[144:145]
	v_add_u32_e32 v104, -1, v103
	v_add_u32_e32 v105, 1, v103
	v_fma_f32 v106, -v104, v103, v102
	v_fma_f32 v107, -v105, v103, v102
	v_cmp_ge_f32_e64 s[0:1], 0, v106
	s_nop 1
	v_cndmask_b32_e64 v103, v103, v104, s[0:1]
	v_cmp_lt_f32_e64 s[0:1], 0, v107
	s_nop 1
	v_cndmask_b32_e64 v103, v103, v105, s[0:1]
	v_mul_f32_e32 v104, 0x37800000, v103
	v_cndmask_b32_e32 v103, v103, v104, vcc
	v_cmp_class_f32_e32 vcc, v102, v155
	s_nop 1
	v_cndmask_b32_e32 v102, v103, v102, vcc
	v_div_scale_f32 v103, s[0:1], v102, v102, 1.0
	v_rcp_f32_e32 v104, v103
	v_div_scale_f32 v105, vcc, 1.0, v102, 1.0
	v_fma_f32 v106, -v103, v104, 1.0
	v_fmac_f32_e32 v104, v106, v104
	v_mul_f32_e32 v106, v105, v104
	v_fma_f32 v107, -v103, v106, v105
	v_fmac_f32_e32 v106, v107, v104
	v_fma_f32 v103, -v103, v106, v105
	v_div_fmas_f32 v103, v103, v104, v106
	v_div_fixup_f32 v102, v103, v102, 1.0
	v_pk_mul_f32 v[94:95], v[94:95], v[102:103] op_sel_hi:[1,0]
	v_pk_mul_f32 v[92:93], v[92:93], v[102:103] op_sel_hi:[1,0]
	v_pk_mul_f32 v[90:91], v[90:91], v[102:103] op_sel_hi:[1,0]
	v_pk_mul_f32 v[88:89], v[88:89], v[102:103] op_sel_hi:[1,0]
	v_pk_mul_f32 v[82:83], v[82:83], v[102:103] op_sel_hi:[1,0]
	v_pk_mul_f32 v[80:81], v[80:81], v[102:103] op_sel_hi:[1,0]
	v_pk_mul_f32 v[86:87], v[86:87], v[102:103] op_sel_hi:[1,0]
	v_pk_mul_f32 v[84:85], v[84:85], v[102:103] op_sel_hi:[1,0]
	v_max_f32_e32 v92, 0, v92
	v_max_f32_e32 v88, 0, v88
	v_max_f32_e32 v93, 0, v93
	v_max_f32_e32 v89, 0, v89
	v_max_f32_e32 v94, 0, v94
	v_max_f32_e32 v90, 0, v90
	v_max_f32_e32 v95, 0, v95
	v_max_f32_e32 v91, 0, v91
	v_max_f32_e32 v80, 0, v80
	v_max_f32_e32 v81, 0, v81
	v_max_f32_e32 v82, 0, v82
	v_max_f32_e32 v83, 0, v83
	v_max_f32_e32 v84, 0, v84
	v_max_f32_e32 v85, 0, v85
	v_max_f32_e32 v86, 0, v86
	v_max_f32_e32 v87, 0, v87
	v_mul_f32_e32 v92, v92, v92
	v_mul_f32_e32 v88, v88, v88
	v_mul_f32_e32 v93, v93, v93
	v_mul_f32_e32 v89, v89, v89
	v_mul_f32_e32 v94, v94, v94
	v_mul_f32_e32 v90, v90, v90
	v_mul_f32_e32 v95, v95, v95
	v_mul_f32_e32 v91, v91, v91
	v_mul_f32_e32 v102, v80, v80
	v_mul_f32_e32 v103, v81, v81
	v_mul_f32_e32 v104, v82, v82
	v_mul_f32_e32 v105, v83, v83
	v_cvt_pk_bf16_f32 v80, v92, v93
	v_cvt_pk_bf16_f32 v81, v94, v95
	v_cvt_pk_bf16_f32 v82, v88, v89
	v_cvt_pk_bf16_f32 v83, v90, v91
	v_mul_f32_e32 v84, v84, v84
	v_mul_f32_e32 v85, v85, v85
	v_mul_f32_e32 v86, v86, v86
	v_mul_f32_e32 v87, v87, v87
	global_store_dwordx4 v[98:99], v[80:83], off nt
	s_nop 1
	v_cvt_pk_bf16_f32 v80, v84, v85
	v_cvt_pk_bf16_f32 v81, v86, v87
	v_cvt_pk_bf16_f32 v82, v102, v103
	v_cvt_pk_bf16_f32 v83, v104, v105
	global_store_dwordx4 v[98:99], v[80:83], off offset:256 nt
	s_nop 1
	v_mov_b32_e32 v82, v183
	s_nop 0
	v_or_b32_e32 v80, 0x80, v146
	v_ashrrev_i32_e32 v81, 31, v80
	v_lshl_add_u64 v[84:85], v[80:81], 2, s[14:15]
	v_fmamk_f32 v82, v82, 0x3a000000, v154
	v_mul_f32_e32 v83, 0x4f800000, v82
	v_cmp_gt_f32_e32 vcc, s62, v82
	s_nop 1
	v_cndmask_b32_e32 v86, v82, v83, vcc
	v_sqrt_f32_e32 v87, v86
	v_lshlrev_b64 v[82:83], 14, v[96:97]
	v_lshl_add_u64 v[82:83], s[12:13], 0, v[82:83]
	v_lshl_add_u64 v[82:83], v[82:83], 0, v[144:145]
	v_add_u32_e32 v88, -1, v87
	v_add_u32_e32 v89, 1, v87
	v_fma_f32 v90, -v88, v87, v86
	v_fma_f32 v91, -v89, v87, v86
	v_cmp_ge_f32_e64 s[0:1], 0, v90
	s_nop 1
	v_cndmask_b32_e64 v87, v87, v88, s[0:1]
	v_cmp_lt_f32_e64 s[0:1], 0, v91
	s_nop 1
	v_cndmask_b32_e64 v87, v87, v89, s[0:1]
	v_mul_f32_e32 v88, 0x37800000, v87
	v_cndmask_b32_e32 v87, v87, v88, vcc
	v_cmp_class_f32_e32 vcc, v86, v155
	s_nop 1
	v_cndmask_b32_e32 v86, v87, v86, vcc
	v_div_scale_f32 v87, s[0:1], v86, v86, 1.0
	v_rcp_f32_e32 v88, v87
	v_div_scale_f32 v89, vcc, 1.0, v86, 1.0
	v_fma_f32 v90, -v87, v88, 1.0
	v_fmac_f32_e32 v88, v90, v88
	v_mul_f32_e32 v90, v89, v88
	v_fma_f32 v91, -v87, v90, v89
	v_fmac_f32_e32 v90, v91, v88
	v_fma_f32 v87, -v87, v90, v89
	v_div_fmas_f32 v87, v87, v88, v90
	v_div_fixup_f32 v86, v87, v86, 1.0
	v_pk_mul_f32 v[78:79], v[78:79], v[86:87] op_sel_hi:[1,0]
	v_pk_mul_f32 v[76:77], v[76:77], v[86:87] op_sel_hi:[1,0]
	v_pk_mul_f32 v[74:75], v[74:75], v[86:87] op_sel_hi:[1,0]
	v_pk_mul_f32 v[72:73], v[72:73], v[86:87] op_sel_hi:[1,0]
	v_pk_mul_f32 v[66:67], v[66:67], v[86:87] op_sel_hi:[1,0]
	v_pk_mul_f32 v[64:65], v[64:65], v[86:87] op_sel_hi:[1,0]
	v_pk_mul_f32 v[70:71], v[70:71], v[86:87] op_sel_hi:[1,0]
	v_pk_mul_f32 v[68:69], v[68:69], v[86:87] op_sel_hi:[1,0]
	v_max_f32_e32 v76, 0, v76
	v_max_f32_e32 v72, 0, v72
	v_max_f32_e32 v77, 0, v77
	v_max_f32_e32 v73, 0, v73
	v_max_f32_e32 v78, 0, v78
	v_max_f32_e32 v74, 0, v74
	v_max_f32_e32 v79, 0, v79
	v_max_f32_e32 v75, 0, v75
	v_max_f32_e32 v64, 0, v64
	v_max_f32_e32 v65, 0, v65
	v_max_f32_e32 v66, 0, v66
	v_max_f32_e32 v67, 0, v67
	v_max_f32_e32 v68, 0, v68
	v_max_f32_e32 v69, 0, v69
	v_max_f32_e32 v70, 0, v70
	v_max_f32_e32 v71, 0, v71
	v_mul_f32_e32 v76, v76, v76
	v_mul_f32_e32 v72, v72, v72
	v_mul_f32_e32 v77, v77, v77
	v_mul_f32_e32 v73, v73, v73
	v_mul_f32_e32 v78, v78, v78
	v_mul_f32_e32 v74, v74, v74
	v_mul_f32_e32 v79, v79, v79
	v_mul_f32_e32 v75, v75, v75
	v_mul_f32_e32 v86, v64, v64
	v_mul_f32_e32 v87, v65, v65
	v_mul_f32_e32 v88, v66, v66
	v_mul_f32_e32 v89, v67, v67
	v_cvt_pk_bf16_f32 v64, v76, v77
	v_cvt_pk_bf16_f32 v65, v78, v79
	v_cvt_pk_bf16_f32 v66, v72, v73
	v_cvt_pk_bf16_f32 v67, v74, v75
	v_mul_f32_e32 v68, v68, v68
	v_mul_f32_e32 v69, v69, v69
	v_mul_f32_e32 v70, v70, v70
	v_mul_f32_e32 v71, v71, v71
	global_store_dwordx4 v[82:83], v[64:67], off nt
	s_nop 1
	v_cvt_pk_bf16_f32 v64, v68, v69
	v_cvt_pk_bf16_f32 v65, v70, v71
	v_cvt_pk_bf16_f32 v66, v86, v87
	v_cvt_pk_bf16_f32 v67, v88, v89
	global_store_dwordx4 v[82:83], v[64:67], off offset:256 nt
	s_nop 1
	v_mov_b32_e32 v66, v184
	s_nop 0
	v_or_b32_e32 v64, 0x90, v146
	v_ashrrev_i32_e32 v65, 31, v64
	v_lshl_add_u64 v[68:69], v[64:65], 2, s[14:15]
	v_fmamk_f32 v66, v66, 0x3a000000, v154
	v_mul_f32_e32 v67, 0x4f800000, v66
	v_cmp_gt_f32_e32 vcc, s62, v66
	s_nop 1
	v_cndmask_b32_e32 v70, v66, v67, vcc
	v_sqrt_f32_e32 v71, v70
	v_lshlrev_b64 v[66:67], 14, v[80:81]
	v_lshl_add_u64 v[66:67], s[12:13], 0, v[66:67]
	v_lshl_add_u64 v[66:67], v[66:67], 0, v[144:145]
	v_add_u32_e32 v72, -1, v71
	v_add_u32_e32 v73, 1, v71
	v_fma_f32 v74, -v72, v71, v70
	v_fma_f32 v75, -v73, v71, v70
	v_cmp_ge_f32_e64 s[0:1], 0, v74
	s_nop 1
	v_cndmask_b32_e64 v71, v71, v72, s[0:1]
	v_cmp_lt_f32_e64 s[0:1], 0, v75
	s_nop 1
	v_cndmask_b32_e64 v71, v71, v73, s[0:1]
	v_mul_f32_e32 v72, 0x37800000, v71
	v_cndmask_b32_e32 v71, v71, v72, vcc
	v_cmp_class_f32_e32 vcc, v70, v155
	s_nop 1
	v_cndmask_b32_e32 v70, v71, v70, vcc
	v_div_scale_f32 v71, s[0:1], v70, v70, 1.0
	v_rcp_f32_e32 v72, v71
	v_div_scale_f32 v73, vcc, 1.0, v70, 1.0
	v_fma_f32 v74, -v71, v72, 1.0
	v_fmac_f32_e32 v72, v74, v72
	v_mul_f32_e32 v74, v73, v72
	v_fma_f32 v75, -v71, v74, v73
	v_fmac_f32_e32 v74, v75, v72
	v_fma_f32 v71, -v71, v74, v73
	v_div_fmas_f32 v71, v71, v72, v74
	v_div_fixup_f32 v70, v71, v70, 1.0
	v_pk_mul_f32 v[62:63], v[62:63], v[70:71] op_sel_hi:[1,0]
	v_pk_mul_f32 v[60:61], v[60:61], v[70:71] op_sel_hi:[1,0]
	v_pk_mul_f32 v[58:59], v[58:59], v[70:71] op_sel_hi:[1,0]
	v_pk_mul_f32 v[56:57], v[56:57], v[70:71] op_sel_hi:[1,0]
	v_pk_mul_f32 v[50:51], v[50:51], v[70:71] op_sel_hi:[1,0]
	v_pk_mul_f32 v[48:49], v[48:49], v[70:71] op_sel_hi:[1,0]
	v_pk_mul_f32 v[54:55], v[54:55], v[70:71] op_sel_hi:[1,0]
	v_pk_mul_f32 v[52:53], v[52:53], v[70:71] op_sel_hi:[1,0]
	v_max_f32_e32 v60, 0, v60
	v_max_f32_e32 v56, 0, v56
	v_max_f32_e32 v61, 0, v61
	v_max_f32_e32 v57, 0, v57
	v_max_f32_e32 v62, 0, v62
	v_max_f32_e32 v58, 0, v58
	v_max_f32_e32 v63, 0, v63
	v_max_f32_e32 v59, 0, v59
	v_max_f32_e32 v48, 0, v48
	v_max_f32_e32 v49, 0, v49
	v_max_f32_e32 v50, 0, v50
	v_max_f32_e32 v51, 0, v51
	v_max_f32_e32 v52, 0, v52
	v_max_f32_e32 v53, 0, v53
	v_max_f32_e32 v54, 0, v54
	v_max_f32_e32 v55, 0, v55
	v_mul_f32_e32 v60, v60, v60
	v_mul_f32_e32 v56, v56, v56
	v_mul_f32_e32 v61, v61, v61
	v_mul_f32_e32 v57, v57, v57
	v_mul_f32_e32 v62, v62, v62
	v_mul_f32_e32 v58, v58, v58
	v_mul_f32_e32 v63, v63, v63
	v_mul_f32_e32 v59, v59, v59
	v_mul_f32_e32 v70, v48, v48
	v_mul_f32_e32 v71, v49, v49
	v_mul_f32_e32 v72, v50, v50
	v_mul_f32_e32 v73, v51, v51
	v_cvt_pk_bf16_f32 v48, v60, v61
	v_cvt_pk_bf16_f32 v49, v62, v63
	v_cvt_pk_bf16_f32 v50, v56, v57
	v_cvt_pk_bf16_f32 v51, v58, v59
	v_mul_f32_e32 v52, v52, v52
	v_mul_f32_e32 v53, v53, v53
	v_mul_f32_e32 v54, v54, v54
	v_mul_f32_e32 v55, v55, v55
	global_store_dwordx4 v[66:67], v[48:51], off nt
	s_nop 1
	v_cvt_pk_bf16_f32 v48, v52, v53
	v_cvt_pk_bf16_f32 v49, v54, v55
	v_cvt_pk_bf16_f32 v50, v70, v71
	v_cvt_pk_bf16_f32 v51, v72, v73
	global_store_dwordx4 v[66:67], v[48:51], off offset:256 nt
	s_nop 1
	v_mov_b32_e32 v50, v185
	s_nop 0
	v_or_b32_e32 v48, 0xa0, v146
	v_ashrrev_i32_e32 v49, 31, v48
	v_lshl_add_u64 v[52:53], v[48:49], 2, s[14:15]
	v_fmamk_f32 v50, v50, 0x3a000000, v154
	v_mul_f32_e32 v51, 0x4f800000, v50
	v_cmp_gt_f32_e32 vcc, s62, v50
	s_nop 1
	v_cndmask_b32_e32 v54, v50, v51, vcc
	v_sqrt_f32_e32 v55, v54
	v_lshlrev_b64 v[50:51], 14, v[64:65]
	v_lshl_add_u64 v[50:51], s[12:13], 0, v[50:51]
	v_lshl_add_u64 v[50:51], v[50:51], 0, v[144:145]
	v_add_u32_e32 v56, -1, v55
	v_add_u32_e32 v57, 1, v55
	v_fma_f32 v58, -v56, v55, v54
	v_fma_f32 v59, -v57, v55, v54
	v_cmp_ge_f32_e64 s[0:1], 0, v58
	s_nop 1
	v_cndmask_b32_e64 v55, v55, v56, s[0:1]
	v_cmp_lt_f32_e64 s[0:1], 0, v59
	s_nop 1
	v_cndmask_b32_e64 v55, v55, v57, s[0:1]
	v_mul_f32_e32 v56, 0x37800000, v55
	v_cndmask_b32_e32 v55, v55, v56, vcc
	v_cmp_class_f32_e32 vcc, v54, v155
	s_nop 1
	v_cndmask_b32_e32 v54, v55, v54, vcc
	v_div_scale_f32 v55, s[0:1], v54, v54, 1.0
	v_rcp_f32_e32 v56, v55
	v_div_scale_f32 v57, vcc, 1.0, v54, 1.0
	v_fma_f32 v58, -v55, v56, 1.0
	v_fmac_f32_e32 v56, v58, v56
	v_mul_f32_e32 v58, v57, v56
	v_fma_f32 v59, -v55, v58, v57
	v_fmac_f32_e32 v58, v59, v56
	v_fma_f32 v55, -v55, v58, v57
	v_div_fmas_f32 v55, v55, v56, v58
	v_div_fixup_f32 v54, v55, v54, 1.0
	v_pk_mul_f32 v[46:47], v[46:47], v[54:55] op_sel_hi:[1,0]
	v_pk_mul_f32 v[44:45], v[44:45], v[54:55] op_sel_hi:[1,0]
	v_pk_mul_f32 v[42:43], v[42:43], v[54:55] op_sel_hi:[1,0]
	v_pk_mul_f32 v[40:41], v[40:41], v[54:55] op_sel_hi:[1,0]
	v_pk_mul_f32 v[34:35], v[34:35], v[54:55] op_sel_hi:[1,0]
	v_pk_mul_f32 v[32:33], v[32:33], v[54:55] op_sel_hi:[1,0]
	v_pk_mul_f32 v[38:39], v[38:39], v[54:55] op_sel_hi:[1,0]
	v_pk_mul_f32 v[36:37], v[36:37], v[54:55] op_sel_hi:[1,0]
	v_max_f32_e32 v44, 0, v44
	v_max_f32_e32 v40, 0, v40
	v_max_f32_e32 v45, 0, v45
	v_max_f32_e32 v41, 0, v41
	v_max_f32_e32 v46, 0, v46
	v_max_f32_e32 v42, 0, v42
	v_max_f32_e32 v47, 0, v47
	v_max_f32_e32 v43, 0, v43
	v_max_f32_e32 v32, 0, v32
	v_max_f32_e32 v33, 0, v33
	v_max_f32_e32 v34, 0, v34
	v_max_f32_e32 v35, 0, v35
	v_max_f32_e32 v36, 0, v36
	v_max_f32_e32 v37, 0, v37
	v_max_f32_e32 v38, 0, v38
	v_max_f32_e32 v39, 0, v39
	v_mul_f32_e32 v44, v44, v44
	v_mul_f32_e32 v40, v40, v40
	v_mul_f32_e32 v45, v45, v45
	v_mul_f32_e32 v41, v41, v41
	v_mul_f32_e32 v46, v46, v46
	v_mul_f32_e32 v42, v42, v42
	v_mul_f32_e32 v47, v47, v47
	v_mul_f32_e32 v43, v43, v43
	v_mul_f32_e32 v54, v32, v32
	v_mul_f32_e32 v55, v33, v33
	v_mul_f32_e32 v56, v34, v34
	v_mul_f32_e32 v57, v35, v35
	v_cvt_pk_bf16_f32 v32, v44, v45
	v_cvt_pk_bf16_f32 v33, v46, v47
	v_cvt_pk_bf16_f32 v34, v40, v41
	v_cvt_pk_bf16_f32 v35, v42, v43
	v_mul_f32_e32 v36, v36, v36
	v_mul_f32_e32 v37, v37, v37
	v_mul_f32_e32 v38, v38, v38
	v_mul_f32_e32 v39, v39, v39
	global_store_dwordx4 v[50:51], v[32:35], off nt
	s_nop 1
	v_cvt_pk_bf16_f32 v32, v36, v37
	v_cvt_pk_bf16_f32 v33, v38, v39
	v_cvt_pk_bf16_f32 v34, v54, v55
	v_cvt_pk_bf16_f32 v35, v56, v57
	global_store_dwordx4 v[50:51], v[32:35], off offset:256 nt
	s_nop 1
	v_mov_b32_e32 v34, v186
	s_nop 0
	v_or_b32_e32 v32, 0xb0, v146
	v_ashrrev_i32_e32 v33, 31, v32
	v_lshl_add_u64 v[36:37], v[32:33], 2, s[14:15]
	v_fmamk_f32 v34, v34, 0x3a000000, v154
	v_mul_f32_e32 v35, 0x4f800000, v34
	v_cmp_gt_f32_e32 vcc, s62, v34
	s_nop 1
	v_cndmask_b32_e32 v38, v34, v35, vcc
	v_sqrt_f32_e32 v39, v38
	v_lshlrev_b64 v[34:35], 14, v[48:49]
	v_lshl_add_u64 v[34:35], s[12:13], 0, v[34:35]
	v_lshl_add_u64 v[34:35], v[34:35], 0, v[144:145]
	v_add_u32_e32 v40, -1, v39
	v_add_u32_e32 v41, 1, v39
	v_fma_f32 v42, -v40, v39, v38
	v_fma_f32 v43, -v41, v39, v38
	v_cmp_ge_f32_e64 s[0:1], 0, v42
	s_nop 1
	v_cndmask_b32_e64 v39, v39, v40, s[0:1]
	v_cmp_lt_f32_e64 s[0:1], 0, v43
	s_nop 1
	v_cndmask_b32_e64 v39, v39, v41, s[0:1]
	v_mul_f32_e32 v40, 0x37800000, v39
	v_cndmask_b32_e32 v39, v39, v40, vcc
	v_cmp_class_f32_e32 vcc, v38, v155
	s_nop 1
	v_cndmask_b32_e32 v38, v39, v38, vcc
	v_div_scale_f32 v39, s[0:1], v38, v38, 1.0
	v_rcp_f32_e32 v40, v39
	v_div_scale_f32 v41, vcc, 1.0, v38, 1.0
	v_fma_f32 v42, -v39, v40, 1.0
	v_fmac_f32_e32 v40, v42, v40
	v_mul_f32_e32 v42, v41, v40
	v_fma_f32 v43, -v39, v42, v41
	v_fmac_f32_e32 v42, v43, v40
	v_fma_f32 v39, -v39, v42, v41
	v_div_fmas_f32 v39, v39, v40, v42
	v_div_fixup_f32 v38, v39, v38, 1.0
	v_pk_mul_f32 v[30:31], v[30:31], v[38:39] op_sel_hi:[1,0]
	v_pk_mul_f32 v[28:29], v[28:29], v[38:39] op_sel_hi:[1,0]
	v_pk_mul_f32 v[26:27], v[26:27], v[38:39] op_sel_hi:[1,0]
	v_pk_mul_f32 v[24:25], v[24:25], v[38:39] op_sel_hi:[1,0]
	v_pk_mul_f32 v[18:19], v[18:19], v[38:39] op_sel_hi:[1,0]
	v_pk_mul_f32 v[16:17], v[16:17], v[38:39] op_sel_hi:[1,0]
	v_pk_mul_f32 v[22:23], v[22:23], v[38:39] op_sel_hi:[1,0]
	v_pk_mul_f32 v[20:21], v[20:21], v[38:39] op_sel_hi:[1,0]
	v_max_f32_e32 v28, 0, v28
	v_max_f32_e32 v24, 0, v24
	v_max_f32_e32 v29, 0, v29
	v_max_f32_e32 v25, 0, v25
	v_max_f32_e32 v30, 0, v30
	v_max_f32_e32 v26, 0, v26
	v_max_f32_e32 v31, 0, v31
	v_max_f32_e32 v27, 0, v27
	v_max_f32_e32 v16, 0, v16
	v_max_f32_e32 v17, 0, v17
	v_max_f32_e32 v18, 0, v18
	v_max_f32_e32 v19, 0, v19
	v_max_f32_e32 v20, 0, v20
	v_max_f32_e32 v21, 0, v21
	v_max_f32_e32 v22, 0, v22
	v_max_f32_e32 v23, 0, v23
	v_mul_f32_e32 v28, v28, v28
	v_mul_f32_e32 v24, v24, v24
	v_mul_f32_e32 v29, v29, v29
	v_mul_f32_e32 v25, v25, v25
	v_mul_f32_e32 v30, v30, v30
	v_mul_f32_e32 v26, v26, v26
	v_mul_f32_e32 v31, v31, v31
	v_mul_f32_e32 v27, v27, v27
	v_mul_f32_e32 v38, v16, v16
	v_mul_f32_e32 v39, v17, v17
	v_mul_f32_e32 v40, v18, v18
	v_mul_f32_e32 v41, v19, v19
	v_cvt_pk_bf16_f32 v16, v28, v29
	v_cvt_pk_bf16_f32 v17, v30, v31
	v_cvt_pk_bf16_f32 v18, v24, v25
	v_cvt_pk_bf16_f32 v19, v26, v27
	v_mul_f32_e32 v20, v20, v20
	v_mul_f32_e32 v21, v21, v21
	v_mul_f32_e32 v22, v22, v22
	v_mul_f32_e32 v23, v23, v23
	global_store_dwordx4 v[34:35], v[16:19], off nt
	s_nop 1
	v_cvt_pk_bf16_f32 v16, v20, v21
	v_cvt_pk_bf16_f32 v17, v22, v23
	v_cvt_pk_bf16_f32 v18, v38, v39
	v_cvt_pk_bf16_f32 v19, v40, v41
	global_store_dwordx4 v[34:35], v[16:19], off offset:256 nt
	s_nop 1
	v_mov_b32_e32 v16, v187
	v_fmamk_f32 v16, v16, 0x3a000000, v154
	v_mul_f32_e32 v17, 0x4f800000, v16
	v_cmp_gt_f32_e32 vcc, s62, v16
	s_nop 1
	v_cndmask_b32_e32 v18, v16, v17, vcc
	v_sqrt_f32_e32 v19, v18
	v_lshlrev_b64 v[16:17], 14, v[32:33]
	v_lshl_add_u64 v[16:17], s[12:13], 0, v[16:17]
	v_lshl_add_u64 v[16:17], v[16:17], 0, v[144:145]
	v_add_u32_e32 v20, -1, v19
	v_add_u32_e32 v21, 1, v19
	v_fma_f32 v22, -v20, v19, v18
	v_fma_f32 v23, -v21, v19, v18
	v_cmp_ge_f32_e64 s[0:1], 0, v22
	s_nop 1
	v_cndmask_b32_e64 v19, v19, v20, s[0:1]
	v_cmp_lt_f32_e64 s[0:1], 0, v23
	s_nop 1
	v_cndmask_b32_e64 v19, v19, v21, s[0:1]
	v_mul_f32_e32 v20, 0x37800000, v19
	v_cndmask_b32_e32 v19, v19, v20, vcc
	v_cmp_class_f32_e32 vcc, v18, v155
	s_nop 1
	v_cndmask_b32_e32 v18, v19, v18, vcc
	v_div_scale_f32 v19, s[0:1], v18, v18, 1.0
	v_rcp_f32_e32 v20, v19
	v_div_scale_f32 v21, vcc, 1.0, v18, 1.0
	s_mov_b64 s[0:1], -1
	v_fma_f32 v22, -v19, v20, 1.0
	v_fmac_f32_e32 v20, v22, v20
	v_mul_f32_e32 v22, v21, v20
	v_fma_f32 v23, -v19, v22, v21
	v_fmac_f32_e32 v22, v23, v20
	v_fma_f32 v19, -v19, v22, v21
	v_div_fmas_f32 v19, v19, v20, v22
	v_div_fixup_f32 v18, v19, v18, 1.0
	v_pk_mul_f32 v[14:15], v[14:15], v[18:19] op_sel_hi:[1,0]
	v_pk_mul_f32 v[12:13], v[12:13], v[18:19] op_sel_hi:[1,0]
	v_pk_mul_f32 v[10:11], v[10:11], v[18:19] op_sel_hi:[1,0]
	v_pk_mul_f32 v[8:9], v[8:9], v[18:19] op_sel_hi:[1,0]
	v_pk_mul_f32 v[2:3], v[2:3], v[18:19] op_sel_hi:[1,0]
	v_pk_mul_f32 v[0:1], v[0:1], v[18:19] op_sel_hi:[1,0]
	v_pk_mul_f32 v[6:7], v[6:7], v[18:19] op_sel_hi:[1,0]
	v_pk_mul_f32 v[4:5], v[4:5], v[18:19] op_sel_hi:[1,0]
	v_max_f32_e32 v12, 0, v12
	v_max_f32_e32 v8, 0, v8
	v_max_f32_e32 v13, 0, v13
	v_max_f32_e32 v9, 0, v9
	v_max_f32_e32 v14, 0, v14
	v_max_f32_e32 v10, 0, v10
	v_max_f32_e32 v15, 0, v15
	v_max_f32_e32 v11, 0, v11
	v_max_f32_e32 v0, 0, v0
	v_max_f32_e32 v1, 0, v1
	v_max_f32_e32 v2, 0, v2
	v_max_f32_e32 v3, 0, v3
	s_andn2_b64 vcc, exec, s[6:7]
	v_max_f32_e32 v4, 0, v4
	v_max_f32_e32 v5, 0, v5
	v_max_f32_e32 v6, 0, v6
	v_max_f32_e32 v7, 0, v7
	v_mul_f32_e32 v12, v12, v12
	v_mul_f32_e32 v8, v8, v8
	v_mul_f32_e32 v13, v13, v13
	v_mul_f32_e32 v9, v9, v9
	v_mul_f32_e32 v14, v14, v14
	v_mul_f32_e32 v10, v10, v10
	v_mul_f32_e32 v15, v15, v15
	v_mul_f32_e32 v11, v11, v11
	v_mul_f32_e32 v18, v0, v0
	v_mul_f32_e32 v19, v1, v1
	v_mul_f32_e32 v20, v2, v2
	v_mul_f32_e32 v21, v3, v3
	v_cvt_pk_bf16_f32 v0, v12, v13
	v_cvt_pk_bf16_f32 v1, v14, v15
	v_cvt_pk_bf16_f32 v2, v8, v9
	v_cvt_pk_bf16_f32 v3, v10, v11
	v_mul_f32_e32 v4, v4, v4
	v_mul_f32_e32 v5, v5, v5
	v_mul_f32_e32 v6, v6, v6
	v_mul_f32_e32 v7, v7, v7
	global_store_dwordx4 v[16:17], v[0:3], off nt
	s_nop 1
	v_cvt_pk_bf16_f32 v0, v4, v5
	v_cvt_pk_bf16_f32 v1, v6, v7
	v_cvt_pk_bf16_f32 v2, v18, v19
	v_cvt_pk_bf16_f32 v3, v20, v21
	global_store_dwordx4 v[16:17], v[0:3], off offset:256 nt
	s_cbranch_vccnz .LBB0_1513
	s_andn2_b64 vcc, exec, s[10:11]
	s_cbranch_vccnz .LBB0_1512
	s_barrier
	s_branch .LBB0_1512
